# first two counted waits of a P1 unit relaxed by the exact store count (16) after the three epilogue variants that issue 16 unconditional stores, so store acknowledgements no longer gate the first segm
# baseline (speedup 1.0000x reference)
; __global__ void __launch_bounds__(NWAVES * 64, 2) mega_fwd(Args args) {
;     ...
;     if (IN(1)) {
;         pg8::Gemm g{(const bf16*)(P.ws + WS_XB), (const bf16*)(P.ws + WS_WIN), MROWS, INC, DM}; const bool lv = (F.MISC[11] == 1u) && F.G == 256 && IN(0);
;         pg8::StaticOrder S; S.init(MROWS, INC, F.G, lv ? (int)F.MISC[10] * 8 + (int)bar.x : (int)blockIdx.x, 2);
.LBB0_128:
	s_mov_b32 s100, 0
	s_cmp_lt_i32 s52, 2
	s_cselect_b64 s[0:1], -1, 0
	s_cmp_gt_i32 s53, 1
	s_cselect_b64 s[4:5], -1, 0
	s_and_b64 s[0:1], s[0:1], s[4:5]
	s_andn2_b64 vcc, exec, s[0:1]
	s_cbranch_vccnz .LBB0_315
	s_add_i32 s0, 0, 0x27d6c
	v_mov_b32_e32 v1, s0
	ds_read_b32 v1, v1
	s_waitcnt lgkmcnt(0)
	v_readfirstlane_b32 s0, v1
	s_cmp_eq_u32 s0, 1
	s_cselect_b64 s[0:1], -1, 0
	s_cmpk_eq_i32 s3, 0x100
	s_cselect_b64 s[4:5], -1, 0
	s_and_b64 s[0:1], s[4:5], s[0:1]
	s_and_b64 s[0:1], s[10:11], s[0:1]
	s_xor_b64 s[18:19], s[0:1], -1
	s_and_b64 vcc, exec, s[18:19]
	s_cbranch_vccnz .LBB0_131
	s_add_i32 s0, 0, 0x27d68
	v_mov_b32_e32 v1, s0
	ds_read_b32 v1, v1
	s_waitcnt lgkmcnt(0)
	v_readfirstlane_b32 s0, v1
	s_lshl_b32 s0, s0, 3
	s_add_i32 s96, s0, s72

; #define PG8_STAGE(bufoff, gbase, voff) do { _Pragma("unroll") for (int _i = 0; _i < 2; ++_i) \
;         __builtin_amdgcn_global_load_lds((const unsigned*)((const char*)(gbase) + (voff)[_i]), (PG8_LAS unsigned*)(lds + (bufoff) + ldsw + _i * 8192), 16, 0, 0); } while (0)
; #define PG8_LDA(dst, b, h) do { _Pragma("unroll") for (int m = 0; m < 4; ++m) _Pragma("unroll") for (int k = 0; k < 2; ++k) dst[m][k] = *(const PG8_LAS bf16x8*)(lds + PG8_SA(b, h) + aoff + m * 2048 + k * 1024); } while (0)
; #define PG8_LDB(dst, b, h) do { _Pragma("unroll") for (int n = 0; n < 2; ++n) _Pragma("unroll") for (int k = 0; k < 2; ++k) dst[n][k] = *(const PG8_LAS bf16x8*)(lds + PG8_SB(b, h) + boff + n * 2048 + k * 1024); } while (0)
; #define PG8_WAIT_V(n) asm volatile("s_waitcnt vmcnt(" #n ")" ::: "memory")
; #define PG8_WAIT_L(n) asm volatile("s_waitcnt lgkmcnt(" #n ")" ::: "memory")
; #define PG8_BAR __builtin_amdgcn_s_barrier()
; #define PG8_SCHED __builtin_amdgcn_sched_barrier(0)
; template <class Epi, class Sched, bool ALIGN_EPI = false, bool SP2 = false>
; __device__ __forceinline__ void gemm_phase(PG8_LAS unsigned char* lds, const Gemm g, const Sched& S, const Epi& E) {
;     ...
;         const bool has_next = S.next(ui + 1, nxt);
;         const char* nA = has_next ? (const char*)g.A + (size_t)nxt.pm * tstep : cA; const char* nB = has_next ? (const char*)g.Bt + (size_t)nxt.pn * tstep : cB;
;         for (int t = 0; t < nt; t += 2) {
;             if constexpr (Epi::HAS_MID) { if (t == nt / 2) E.mid(acc, cur, wr, wc, fr, fq); }
;             const bool last = (t == nt - 2);
;             const char* a1 = cA + (size_t)(t + 1) * kstep;
;             const char* a2 = last ? nA : cA + (size_t)(t + 2) * kstep; const char* b2 = last ? nB : cB + (size_t)(t + 2) * kstep;
;             const char* a3 = a2 + kstep; const char* b3 = b2 + kstep;
;             if (last && has_next) S.a_ready(nxt);
;             if constexpr (SP2) {
;             PG8_LDB(B0, 0, 0); PG8_LDB(B1, 0, 1); PG8_SCHED; PG8_LDA(At, 0, 0); PG8_STAGE(PG8_SA(1, 1), a1 + hstep, voffA);
;             PG8_WAIT_V(8); PG8_WAIT_L(0); PG8_BAR; PG8_MMA(0, 0, At, B0); PG8_MMA(0, 1, At, B1); PG8_BAR; PG8_SCHED;
;             PG8_LDA(At, 0, 1); PG8_STAGE(PG8_SB(0, 0), b2, voffB); PG8_STAGE(PG8_SB(0, 1), b2 + hstep, voffB); PG8_STAGE(PG8_SA(0, 0), a2, voffA);
.LBB0_142:
	s_ashr_i32 s81, s80, 31
	s_lshl_b64 s[84:85], s[80:81], 19
	s_add_u32 s84, s98, s84
	s_addc_u32 s85, s99, s85
	s_and_b64 s[86:87], s[8:9], exec
	s_cselect_b32 s1, s85, s89
	s_cselect_b32 s11, s84, s88
	s_ashr_i32 s83, s82, 31
	s_lshl_b64 s[86:87], s[82:83], 19
	s_add_u32 s86, s4, s86
	s_addc_u32 s87, s5, s87
	s_and_b64 s[92:93], s[8:9], exec
	s_cselect_b32 s79, s87, s91
	s_cselect_b32 s81, s86, s90
	s_add_u32 s88, s88, 0x40080
	s_addc_u32 s89, s89, 0
	s_add_u32 s83, s90, 0x100
	s_addc_u32 vcc_lo, s91, 0
	s_mov_b32 vcc_hi, -2
	ds_read_b128 v[130:133], v193
	ds_read_b128 v[134:137], v193 offset:1024
	ds_read_b128 v[138:141], v193 offset:2048
	ds_read_b128 v[142:145], v193 offset:3072
	ds_read_b128 v[166:169], v194
	ds_read_b128 v[170:173], v194 offset:1024
	ds_read_b128 v[174:177], v194 offset:2048
	ds_read_b128 v[178:181], v194 offset:3072
	s_add_u32 s90, s88, 0xfffc0080
	s_addc_u32 s91, s89, -1
	s_cmp_eq_u32 vcc_hi, 12
	s_cselect_b32 s93, s1, s91
	s_cselect_b32 s92, s11, s90
	s_cselect_b32 s91, s79, vcc_lo
	s_cselect_b32 s90, s81, s83
	v_lshl_add_u64 v[190:191], s[88:89], 0, v[156:157]
	s_add_i32 m0, s58, 0xc000
	ds_read_b128 v[182:185], v195
	ds_read_b128 v[186:189], v195 offset:1024
	ds_read_b128 v[200:203], v195 offset:2048
	ds_read_b128 v[204:207], v195 offset:3072
	ds_read_b128 v[208:211], v195 offset:4096
	ds_read_b128 v[212:215], v195 offset:5120
	ds_read_b128 v[216:219], v195 offset:6144
	ds_read_b128 v[220:223], v195 offset:7168
	global_load_lds_dwordx4 v[190:191], off
	v_lshl_add_u64 v[190:191], s[88:89], 0, v[158:159]
	s_add_i32 m0, s58, 0xe000
	s_nop 0
	global_load_lds_dwordx4 v[190:191], off
	s_cmp_eq_u32 s100, 1
	s_cbranch_scc1 .Lp1dr_a
	s_waitcnt vmcnt(8)
.Lp1dr_a_back:
	s_waitcnt lgkmcnt(0)
	s_barrier
	s_setprio 1
	s_waitcnt lgkmcnt(0)
	v_mfma_f32_16x16x32_bf16 v[126:129], v[130:133], v[182:185], 0
	v_mfma_f32_16x16x32_bf16 v[122:125], v[138:141], v[182:185], 0
	v_mfma_f32_16x16x32_bf16 v[110:113], v[130:133], v[200:203], 0
	v_mfma_f32_16x16x32_bf16 v[106:109], v[138:141], v[200:203], 0
	v_mfma_f32_16x16x32_bf16 v[94:97], v[130:133], v[208:211], 0
	v_mfma_f32_16x16x32_bf16 v[90:93], v[138:141], v[208:211], 0
	v_mfma_f32_16x16x32_bf16 v[78:81], v[130:133], v[216:219], 0
	v_mfma_f32_16x16x32_bf16 v[74:77], v[138:141], v[216:219], 0
	v_mfma_f32_16x16x32_bf16 v[126:129], v[134:137], v[186:189], v[126:129]
	v_mfma_f32_16x16x32_bf16 v[122:125], v[142:145], v[186:189], v[122:125]
	v_mfma_f32_16x16x32_bf16 v[110:113], v[134:137], v[204:207], v[110:113]
	v_mfma_f32_16x16x32_bf16 v[106:109], v[142:145], v[204:207], v[106:109]
	v_mfma_f32_16x16x32_bf16 v[94:97], v[134:137], v[212:215], v[94:97]
	v_mfma_f32_16x16x32_bf16 v[90:93], v[142:145], v[212:215], v[90:93]
	v_mfma_f32_16x16x32_bf16 v[78:81], v[134:137], v[220:223], v[78:81]
	v_mfma_f32_16x16x32_bf16 v[74:77], v[142:145], v[220:223], v[74:77]
	v_mfma_f32_16x16x32_bf16 v[118:121], v[166:169], v[182:185], 0
	v_mfma_f32_16x16x32_bf16 v[114:117], v[174:177], v[182:185], 0
	v_mfma_f32_16x16x32_bf16 v[102:105], v[166:169], v[200:203], 0
	v_mfma_f32_16x16x32_bf16 v[98:101], v[174:177], v[200:203], 0
	v_mfma_f32_16x16x32_bf16 v[86:89], v[166:169], v[208:211], 0
	v_mfma_f32_16x16x32_bf16 v[82:85], v[174:177], v[208:211], 0
	v_mfma_f32_16x16x32_bf16 v[70:73], v[166:169], v[216:219], 0
	v_mfma_f32_16x16x32_bf16 v[66:69], v[174:177], v[216:219], 0
	v_mfma_f32_16x16x32_bf16 v[118:121], v[170:173], v[186:189], v[118:121]
	v_mfma_f32_16x16x32_bf16 v[114:117], v[178:181], v[186:189], v[114:117]
	v_mfma_f32_16x16x32_bf16 v[102:105], v[170:173], v[204:207], v[102:105]
	v_mfma_f32_16x16x32_bf16 v[98:101], v[178:181], v[204:207], v[98:101]
	v_mfma_f32_16x16x32_bf16 v[86:89], v[170:173], v[212:215], v[86:89]
	v_mfma_f32_16x16x32_bf16 v[82:85], v[178:181], v[212:215], v[82:85]
	v_mfma_f32_16x16x32_bf16 v[70:73], v[170:173], v[220:223], v[70:73]
	v_mfma_f32_16x16x32_bf16 v[66:69], v[178:181], v[220:223], v[66:69]
	s_setprio 0
	s_barrier
	s_add_i32 s94, s7, s97
	v_lshl_add_u64 v[190:191], s[90:91], 0, v[148:149]
	s_mov_b32 m0, s94
	ds_read_b128 v[182:185], v195 offset:16384
	ds_read_b128 v[186:189], v195 offset:17408
	ds_read_b128 v[200:203], v195 offset:18432
	ds_read_b128 v[204:207], v195 offset:19456
	ds_read_b128 v[208:211], v195 offset:20480
	ds_read_b128 v[212:215], v195 offset:21504
	ds_read_b128 v[216:219], v195 offset:22528
	ds_read_b128 v[220:223], v195 offset:23552
	global_load_lds_dwordx4 v[190:191], off
	s_add_i32 m0, s94, 0x2000
	s_add_u32 s94, s90, 0x40000
	v_lshl_add_u64 v[224:225], s[90:91], 0, v[152:153]
	s_addc_u32 s95, s91, 0
	s_add_i32 s18, s64, s97
	global_load_lds_dwordx4 v[224:225], off
	v_lshl_add_u64 v[226:227], s[94:95], 0, v[148:149]
	s_mov_b32 m0, s18
	v_lshl_add_u64 v[228:229], s[92:93], 0, v[150:151]
	global_load_lds_dwordx4 v[226:227], off
	v_lshl_add_u64 v[226:227], s[94:95], 0, v[152:153]
	s_add_i32 m0, s18, 0x2000
	s_nop 0
	global_load_lds_dwordx4 v[226:227], off
	v_lshl_add_u64 v[226:227], s[92:93], 0, v[146:147]
	s_mov_b32 m0, s58
	s_nop 0
	global_load_lds_dwordx4 v[226:227], off
	s_mov_b32 m0, s59
	s_nop 0
	global_load_lds_dwordx4 v[228:229], off
	s_cmp_eq_u32 s100, 1
	s_cbranch_scc1 .Lp1dr_b
	s_waitcnt vmcnt(8)
; #define PG8_STAGE(bufoff, gbase, voff) do { _Pragma("unroll") for (int _i = 0; _i < 2; ++_i) \
;         __builtin_amdgcn_global_load_lds((const unsigned*)((const char*)(gbase) + (voff)[_i]), (PG8_LAS unsigned*)(lds + (bufoff) + ldsw + _i * 8192), 16, 0, 0); } while (0)
; #define PG8_LDA(dst, b, h) do { _Pragma("unroll") for (int m = 0; m < 4; ++m) _Pragma("unroll") for (int k = 0; k < 2; ++k) dst[m][k] = *(const PG8_LAS bf16x8*)(lds + PG8_SA(b, h) + aoff + m * 2048 + k * 1024); } while (0)
; #define PG8_LDB(dst, b, h) do { _Pragma("unroll") for (int n = 0; n < 2; ++n) _Pragma("unroll") for (int k = 0; k < 2; ++k) dst[n][k] = *(const PG8_LAS bf16x8*)(lds + PG8_SB(b, h) + boff + n * 2048 + k * 1024); } while (0)
; #define PG8_MMA(ai, bj, At, Bt) do { __builtin_amdgcn_s_setprio(1); _Pragma("unroll") for (int m = 0; m < 4; ++m) _Pragma("unroll") for (int n = 0; n < 2; ++n) _Pragma("unroll") for (int k = 0; k < 2; ++k) \
;         acc[ai][bj][m][n] = __builtin_amdgcn_mfma_f32_16x16x32_bf16(Bt[n][k], At[m][k], acc[ai][bj][m][n], 0, 0, 0); __builtin_amdgcn_s_setprio(0); } while (0)
; #define PG8_WAIT_V(n) asm volatile("s_waitcnt vmcnt(" #n ")" ::: "memory")
; #define PG8_WAIT_L(n) asm volatile("s_waitcnt lgkmcnt(" #n ")" ::: "memory")
; #define PG8_BAR __builtin_amdgcn_s_barrier()
; #define PG8_SCHED __builtin_amdgcn_sched_barrier(0)
; template <class Epi, class Sched, bool ALIGN_EPI = false, bool SP2 = false>
; __device__ __forceinline__ void gemm_phase(PG8_LAS unsigned char* lds, const Gemm g, const Sched& S, const Epi& E) {
;     ...
;             PG8_WAIT_V(8); PG8_WAIT_L(0); PG8_BAR; PG8_MMA(1, 0, At, B0); PG8_MMA(1, 1, At, B1); PG8_BAR; PG8_SCHED;
;             PG8_LDB(B0, 1, 0); PG8_LDB(B1, 1, 1); PG8_SCHED; PG8_LDA(At, 1, 0); PG8_STAGE(PG8_SA(0, 1), a2 + hstep, voffA);
;             PG8_WAIT_V(8); PG8_WAIT_L(0); PG8_BAR; PG8_MMA(0, 0, At, B0); PG8_MMA(0, 1, At, B1); PG8_BAR; PG8_SCHED;
.Lp1dr_b_back:
	s_waitcnt lgkmcnt(0)
	s_barrier
	s_setprio 1
	s_waitcnt lgkmcnt(0)
	v_mfma_f32_16x16x32_bf16 v[62:65], v[130:133], v[182:185], 0
	v_mfma_f32_16x16x32_bf16 v[58:61], v[138:141], v[182:185], 0
	v_mfma_f32_16x16x32_bf16 v[46:49], v[130:133], v[200:203], 0
	v_mfma_f32_16x16x32_bf16 v[42:45], v[138:141], v[200:203], 0
	v_mfma_f32_16x16x32_bf16 v[30:33], v[130:133], v[208:211], 0
	v_mfma_f32_16x16x32_bf16 v[26:29], v[138:141], v[208:211], 0
	v_mfma_f32_16x16x32_bf16 v[14:17], v[130:133], v[216:219], 0
	v_mfma_f32_16x16x32_bf16 v[10:13], v[138:141], v[216:219], 0
	v_mfma_f32_16x16x32_bf16 v[62:65], v[134:137], v[186:189], v[62:65]
	v_mfma_f32_16x16x32_bf16 v[58:61], v[142:145], v[186:189], v[58:61]
	v_mfma_f32_16x16x32_bf16 v[46:49], v[134:137], v[204:207], v[46:49]
	v_mfma_f32_16x16x32_bf16 v[42:45], v[142:145], v[204:207], v[42:45]
	v_mfma_f32_16x16x32_bf16 v[30:33], v[134:137], v[212:215], v[30:33]
	v_mfma_f32_16x16x32_bf16 v[26:29], v[142:145], v[212:215], v[26:29]
	v_mfma_f32_16x16x32_bf16 v[14:17], v[134:137], v[220:223], v[14:17]
	v_mfma_f32_16x16x32_bf16 v[10:13], v[142:145], v[220:223], v[10:13]
	v_mfma_f32_16x16x32_bf16 v[54:57], v[166:169], v[182:185], 0
	v_mfma_f32_16x16x32_bf16 v[50:53], v[174:177], v[182:185], 0
	v_mfma_f32_16x16x32_bf16 v[38:41], v[166:169], v[200:203], 0
	v_mfma_f32_16x16x32_bf16 v[34:37], v[174:177], v[200:203], 0
	v_mfma_f32_16x16x32_bf16 v[22:25], v[166:169], v[208:211], 0
	v_mfma_f32_16x16x32_bf16 v[18:21], v[174:177], v[208:211], 0
	v_mfma_f32_16x16x32_bf16 v[6:9], v[166:169], v[216:219], 0
	v_mfma_f32_16x16x32_bf16 v[2:5], v[174:177], v[216:219], 0
	v_mfma_f32_16x16x32_bf16 v[54:57], v[170:173], v[186:189], v[54:57]
	v_mfma_f32_16x16x32_bf16 v[50:53], v[178:181], v[186:189], v[50:53]
	v_mfma_f32_16x16x32_bf16 v[38:41], v[170:173], v[204:207], v[38:41]
	v_mfma_f32_16x16x32_bf16 v[34:37], v[178:181], v[204:207], v[34:37]
	v_mfma_f32_16x16x32_bf16 v[22:25], v[170:173], v[212:215], v[22:25]
	v_mfma_f32_16x16x32_bf16 v[18:21], v[178:181], v[212:215], v[18:21]
	v_mfma_f32_16x16x32_bf16 v[6:9], v[170:173], v[220:223], v[6:9]
	v_mfma_f32_16x16x32_bf16 v[2:5], v[178:181], v[220:223], v[2:5]
	s_setprio 0
	s_barrier
	s_add_i32 s18, 0, 0x18000
	s_add_i32 s94, 0, 0x1c000
	v_add_u32_e32 v142, s18, v192
	v_add_u32_e32 v154, s94, v192
	ds_read_b128 v[130:133], v142
	ds_read_b128 v[134:137], v142 offset:1024
	ds_read_b128 v[138:141], v142 offset:2048
	ds_read_b128 v[142:145], v142 offset:3072
	ds_read_b128 v[166:169], v154
	ds_read_b128 v[170:173], v154 offset:1024
	ds_read_b128 v[174:177], v154 offset:2048
	ds_read_b128 v[178:181], v154 offset:3072
	s_add_u32 s92, s92, 0x40000
	s_addc_u32 s93, s93, 0
	s_mov_b32 m0, s56
	v_lshl_add_u64 v[230:231], s[92:93], 0, v[146:147]
	ds_read_b128 v[182:185], v195 offset:32768
	ds_read_b128 v[186:189], v195 offset:33792
	ds_read_b128 v[200:203], v195 offset:34816
	ds_read_b128 v[204:207], v195 offset:35840
	ds_read_b128 v[208:211], v195 offset:36864
	ds_read_b128 v[212:215], v195 offset:37888
	ds_read_b128 v[216:219], v195 offset:38912
	ds_read_b128 v[220:223], v195 offset:39936
	global_load_lds_dwordx4 v[230:231], off
	v_lshl_add_u64 v[230:231], s[92:93], 0, v[150:151]
	s_mov_b32 m0, s57
	s_nop 0
	global_load_lds_dwordx4 v[230:231], off
	s_waitcnt vmcnt(8)
	s_waitcnt lgkmcnt(0)
	s_barrier
	s_setprio 1
	s_waitcnt lgkmcnt(0)
	v_mfma_f32_16x16x32_bf16 v[126:129], v[130:133], v[182:185], v[126:129]
	v_mfma_f32_16x16x32_bf16 v[122:125], v[138:141], v[182:185], v[122:125]
	v_mfma_f32_16x16x32_bf16 v[110:113], v[130:133], v[200:203], v[110:113]
	v_mfma_f32_16x16x32_bf16 v[106:109], v[138:141], v[200:203], v[106:109]
	v_mfma_f32_16x16x32_bf16 v[94:97], v[130:133], v[208:211], v[94:97]
	v_mfma_f32_16x16x32_bf16 v[90:93], v[138:141], v[208:211], v[90:93]
	v_mfma_f32_16x16x32_bf16 v[78:81], v[130:133], v[216:219], v[78:81]
	v_mfma_f32_16x16x32_bf16 v[74:77], v[138:141], v[216:219], v[74:77]
	v_mfma_f32_16x16x32_bf16 v[126:129], v[134:137], v[186:189], v[126:129]
	v_mfma_f32_16x16x32_bf16 v[122:125], v[142:145], v[186:189], v[122:125]
	v_mfma_f32_16x16x32_bf16 v[110:113], v[134:137], v[204:207], v[110:113]
	v_mfma_f32_16x16x32_bf16 v[106:109], v[142:145], v[204:207], v[106:109]
	v_mfma_f32_16x16x32_bf16 v[94:97], v[134:137], v[212:215], v[94:97]
	v_mfma_f32_16x16x32_bf16 v[90:93], v[142:145], v[212:215], v[90:93]
	v_mfma_f32_16x16x32_bf16 v[78:81], v[134:137], v[220:223], v[78:81]
	v_mfma_f32_16x16x32_bf16 v[74:77], v[142:145], v[220:223], v[74:77]
	v_mfma_f32_16x16x32_bf16 v[118:121], v[166:169], v[182:185], v[118:121]
	v_mfma_f32_16x16x32_bf16 v[114:117], v[174:177], v[182:185], v[114:117]
	v_mfma_f32_16x16x32_bf16 v[102:105], v[166:169], v[200:203], v[102:105]
	v_mfma_f32_16x16x32_bf16 v[98:101], v[174:177], v[200:203], v[98:101]
	v_mfma_f32_16x16x32_bf16 v[86:89], v[166:169], v[208:211], v[86:89]
	v_mfma_f32_16x16x32_bf16 v[82:85], v[174:177], v[208:211], v[82:85]
	v_mfma_f32_16x16x32_bf16 v[70:73], v[166:169], v[216:219], v[70:73]
	v_mfma_f32_16x16x32_bf16 v[66:69], v[174:177], v[216:219], v[66:69]
	v_mfma_f32_16x16x32_bf16 v[118:121], v[170:173], v[186:189], v[118:121]
	v_mfma_f32_16x16x32_bf16 v[114:117], v[178:181], v[186:189], v[114:117]
	v_mfma_f32_16x16x32_bf16 v[102:105], v[170:173], v[204:207], v[102:105]
	v_mfma_f32_16x16x32_bf16 v[98:101], v[178:181], v[204:207], v[98:101]
	v_mfma_f32_16x16x32_bf16 v[86:89], v[170:173], v[212:215], v[86:89]
	v_mfma_f32_16x16x32_bf16 v[82:85], v[178:181], v[212:215], v[82:85]
	v_mfma_f32_16x16x32_bf16 v[70:73], v[170:173], v[220:223], v[70:73]
	v_mfma_f32_16x16x32_bf16 v[66:69], v[178:181], v[220:223], v[66:69]
	s_setprio 0
	s_barrier
; #define PG8_STAGE(bufoff, gbase, voff) do { _Pragma("unroll") for (int _i = 0; _i < 2; ++_i) \
;         __builtin_amdgcn_global_load_lds((const unsigned*)((const char*)(gbase) + (voff)[_i]), (PG8_LAS unsigned*)(lds + (bufoff) + ldsw + _i * 8192), 16, 0, 0); } while (0)
; #define PG8_LDA(dst, b, h) do { _Pragma("unroll") for (int m = 0; m < 4; ++m) _Pragma("unroll") for (int k = 0; k < 2; ++k) dst[m][k] = *(const PG8_LAS bf16x8*)(lds + PG8_SA(b, h) + aoff + m * 2048 + k * 1024); } while (0)
; #define PG8_MMA(ai, bj, At, Bt) do { __builtin_amdgcn_s_setprio(1); _Pragma("unroll") for (int m = 0; m < 4; ++m) _Pragma("unroll") for (int n = 0; n < 2; ++n) _Pragma("unroll") for (int k = 0; k < 2; ++k) \
;         acc[ai][bj][m][n] = __builtin_amdgcn_mfma_f32_16x16x32_bf16(Bt[n][k], At[m][k], acc[ai][bj][m][n], 0, 0, 0); __builtin_amdgcn_s_setprio(0); } while (0)
; #define PG8_WAIT_V(n) asm volatile("s_waitcnt vmcnt(" #n ")" ::: "memory")
; #define PG8_WAIT_L(n) asm volatile("s_waitcnt lgkmcnt(" #n ")" ::: "memory")
; #define PG8_BAR __builtin_amdgcn_s_barrier()
; #define PG8_SCHED __builtin_amdgcn_sched_barrier(0)
; template <class Epi, class Sched, bool ALIGN_EPI = false, bool SP2 = false>
; __device__ __forceinline__ void gemm_phase(PG8_LAS unsigned char* lds, const Gemm g, const Sched& S, const Epi& E) {
;     ...
;             PG8_LDA(At, 1, 1); PG8_STAGE(PG8_SB(1, 0), b3, voffB); PG8_STAGE(PG8_SB(1, 1), b3 + hstep, voffB); PG8_STAGE(PG8_SA(1, 0), a3, voffA);
;             PG8_WAIT_V(8); PG8_WAIT_L(0); PG8_BAR; PG8_MMA(1, 0, At, B0); PG8_MMA(1, 1, At, B1); PG8_BAR; PG8_SCHED;
	s_add_i32 s18, s18, s97
	v_lshl_add_u64 v[190:191], v[190:191], 0, s[74:75]
	s_mov_b32 m0, s18
	ds_read_b128 v[182:185], v195 offset:49152
	ds_read_b128 v[186:189], v195 offset:50176
	ds_read_b128 v[200:203], v195 offset:51200
	ds_read_b128 v[204:207], v195 offset:52224
	ds_read_b128 v[208:211], v195 offset:53248
	ds_read_b128 v[212:215], v195 offset:54272
	ds_read_b128 v[216:219], v195 offset:55296
	ds_read_b128 v[220:223], v195 offset:56320
	global_load_lds_dwordx4 v[190:191], off
	s_add_i32 m0, s18, 0x2000
	s_add_u32 s90, s90, 0x40080
	v_lshl_add_u64 v[190:191], v[224:225], 0, s[74:75]
	s_addc_u32 s91, s91, 0
	s_add_i32 s18, s94, s97
	global_load_lds_dwordx4 v[190:191], off
	v_lshl_add_u64 v[190:191], s[90:91], 0, v[148:149]
	s_mov_b32 m0, s18
	s_nop 0
	global_load_lds_dwordx4 v[190:191], off
	v_lshl_add_u64 v[190:191], s[90:91], 0, v[152:153]
	s_add_i32 m0, s18, 0x2000
	s_nop 0
	global_load_lds_dwordx4 v[190:191], off
	v_lshl_add_u64 v[190:191], v[226:227], 0, s[74:75]
	s_mov_b32 m0, s19
	s_nop 0
	global_load_lds_dwordx4 v[190:191], off
	v_lshl_add_u64 v[190:191], v[228:229], 0, s[74:75]
	s_mov_b32 m0, s66
	s_nop 0
	global_load_lds_dwordx4 v[190:191], off
	s_waitcnt vmcnt(8)
	s_waitcnt lgkmcnt(0)
	s_barrier
	s_setprio 1
	s_waitcnt lgkmcnt(0)
	v_mfma_f32_16x16x32_bf16 v[62:65], v[130:133], v[182:185], v[62:65]
	v_mfma_f32_16x16x32_bf16 v[58:61], v[138:141], v[182:185], v[58:61]
	v_mfma_f32_16x16x32_bf16 v[46:49], v[130:133], v[200:203], v[46:49]
	v_mfma_f32_16x16x32_bf16 v[42:45], v[138:141], v[200:203], v[42:45]
	v_mfma_f32_16x16x32_bf16 v[30:33], v[130:133], v[208:211], v[30:33]
	v_mfma_f32_16x16x32_bf16 v[26:29], v[138:141], v[208:211], v[26:29]
	v_mfma_f32_16x16x32_bf16 v[14:17], v[130:133], v[216:219], v[14:17]
	v_mfma_f32_16x16x32_bf16 v[10:13], v[138:141], v[216:219], v[10:13]
	v_mfma_f32_16x16x32_bf16 v[62:65], v[134:137], v[186:189], v[62:65]
	v_mfma_f32_16x16x32_bf16 v[58:61], v[142:145], v[186:189], v[58:61]
	v_mfma_f32_16x16x32_bf16 v[46:49], v[134:137], v[204:207], v[46:49]
	v_mfma_f32_16x16x32_bf16 v[42:45], v[142:145], v[204:207], v[42:45]
	v_mfma_f32_16x16x32_bf16 v[30:33], v[134:137], v[212:215], v[30:33]
	v_mfma_f32_16x16x32_bf16 v[26:29], v[142:145], v[212:215], v[26:29]
	v_mfma_f32_16x16x32_bf16 v[14:17], v[134:137], v[220:223], v[14:17]
	v_mfma_f32_16x16x32_bf16 v[10:13], v[142:145], v[220:223], v[10:13]
	v_mfma_f32_16x16x32_bf16 v[54:57], v[166:169], v[182:185], v[54:57]
	v_mfma_f32_16x16x32_bf16 v[50:53], v[174:177], v[182:185], v[50:53]
	v_mfma_f32_16x16x32_bf16 v[38:41], v[166:169], v[200:203], v[38:41]
	v_mfma_f32_16x16x32_bf16 v[34:37], v[174:177], v[200:203], v[34:37]
	v_mfma_f32_16x16x32_bf16 v[22:25], v[166:169], v[208:211], v[22:25]
	v_mfma_f32_16x16x32_bf16 v[18:21], v[174:177], v[208:211], v[18:21]
	v_mfma_f32_16x16x32_bf16 v[6:9], v[166:169], v[216:219], v[6:9]
	v_mfma_f32_16x16x32_bf16 v[2:5], v[174:177], v[216:219], v[2:5]
	v_mfma_f32_16x16x32_bf16 v[54:57], v[170:173], v[186:189], v[54:57]
	v_mfma_f32_16x16x32_bf16 v[50:53], v[178:181], v[186:189], v[50:53]
	v_mfma_f32_16x16x32_bf16 v[38:41], v[170:173], v[204:207], v[38:41]
	v_mfma_f32_16x16x32_bf16 v[34:37], v[178:181], v[204:207], v[34:37]
	v_mfma_f32_16x16x32_bf16 v[22:25], v[170:173], v[212:215], v[22:25]
	v_mfma_f32_16x16x32_bf16 v[18:21], v[178:181], v[212:215], v[18:21]
	v_mfma_f32_16x16x32_bf16 v[6:9], v[170:173], v[220:223], v[6:9]
	v_mfma_f32_16x16x32_bf16 v[2:5], v[178:181], v[220:223], v[2:5]
	s_setprio 0
	s_barrier
	s_add_i32 vcc_hi, vcc_hi, 2
	s_add_u32 s88, s88, 0x100
	s_addc_u32 s89, s89, 0
	s_add_u32 s83, s83, 0x100
	s_addc_u32 vcc_lo, vcc_lo, 0
	s_cmp_gt_u32 vcc_hi, 13

; __device__ __forceinline__ unsigned long long rt() { return __builtin_amdgcn_s_memrealtime(); }
; __device__ __forceinline__ u32x4 pack8f(const f32x4 a, const f32x4 b) { u32x4 w; w.x = cvt_pk_bf16(a[0], a[1]); w.y = cvt_pk_bf16(a[2], a[3]); w.z = cvt_pk_bf16(b[0], b[1]); w.w = cvt_pk_bf16(b[2], b[3]); return w; }
;     __device__ __forceinline__ void operator()(f32x4 (&acc)[2][2][4][2], const Unit& u, int wr, int wc, int fr, int fq) const {
;     ...
;         } else {
;             const int j0 = 128 * (pn - 16) + 32 * wc + 8 * fq;
; #pragma unroll
;             for (int ai = 0; ai < 2; ++ai)
; #pragma unroll
;                 for (int m = 0; m < 4; ++m) { const int rl = rl0 + 128 * ai + 16 * m;
;                     f32x4 rt[2], s1[2];
; #pragma unroll
;                     for (int n = 0; n < 2; ++n)
; #pragma unroll
;                         for (int i = 0; i < 4; ++i) {
;                             const float e0 = __builtin_amdgcn_exp2f(fminf(-1.4426950408889634f * acc[ai][0][m][n][i], 60.f)), e1 = __builtin_amdgcn_exp2f(fminf(-1.4426950408889634f * acc[ai][1][m][n][i], 60.f));
;                             rt[n][i] = (1.f + e1) * __builtin_amdgcn_rcpf(1.f + e0); s1[n][i] = __builtin_amdgcn_rcpf(1.f + e1); }
;                     __builtin_nontemporal_store(pack8f(rt[0], rt[1]), (u32x4*)(RT + (size_t)(u.pm * 256 + rl) * DM + j0));
;                     __builtin_nontemporal_store(pack8f(s1[0], s1[1]), (u32x4*)(G1 + (size_t)(u.pm * 256 + rl) * DM + j0));
.LBB0_146:
	s_mov_b32 s100, 0
	s_lshl_b32 s1, s22, 8
	s_ashr_i32 s81, s22, 4
	s_and_b32 s83, s1, 0xf00
	v_mov_b32_e32 v166, v163
	v_mov_b32_e32 v200, v1
	s_cmp_gt_i32 s10, 3
	s_mov_b64 s[88:89], -1
	s_cbranch_scc0 .LBB0_174
	s_cmp_gt_u32 s10, 5
	s_cbranch_scc0 .LBB0_171
	s_cmp_gt_u32 s10, 7
	s_cbranch_scc0 .LBB0_168
	s_cmp_gt_u32 s10, 15
	s_cbranch_scc0 .LBB0_151
	s_mov_b32 s100, 1
	v_mul_f32_e32 v130, 0xbfb8aa3b, v126
	v_min_f32_e32 v130, 0x42700000, v130
	v_exp_f32_e32 v131, v130
	v_mul_f32_e32 v130, 0xbfb8aa3b, v118
	v_min_f32_e32 v130, 0x42700000, v130
	v_exp_f32_e32 v130, v130
	v_add_f32_e32 v131, 1.0, v131
	v_rcp_f32_e32 v132, v131
	v_mul_f32_e32 v131, 0xbfb8aa3b, v127
	v_min_f32_e32 v131, 0x42700000, v131
	v_exp_f32_e32 v133, v131
	v_mul_f32_e32 v131, 0xbfb8aa3b, v119
	v_min_f32_e32 v131, 0x42700000, v131
	v_exp_f32_e32 v131, v131
	v_add_f32_e32 v133, 1.0, v133
	v_rcp_f32_e32 v133, v133
	v_mul_f32_e32 v134, 0xbfb8aa3b, v120
	v_pk_add_f32 v[130:131], v[130:131], 1.0 op_sel_hi:[1,0]
	v_mul_f32_e32 v135, 0xbfb8aa3b, v121
	v_rcp_f32_e32 v154, v130
	v_pk_mul_f32 v[132:133], v[132:133], v[130:131]
	v_mul_f32_e32 v130, 0xbfb8aa3b, v128
	v_min_f32_e32 v130, 0x42700000, v130
	v_exp_f32_e32 v130, v130
	v_min_f32_e32 v134, 0x42700000, v134
	v_min_f32_e32 v135, 0x42700000, v135
	v_exp_f32_e32 v134, v134
	v_add_f32_e32 v130, 1.0, v130
	v_rcp_f32_e32 v136, v130
	v_mul_f32_e32 v130, 0xbfb8aa3b, v129
	v_min_f32_e32 v130, 0x42700000, v130
	v_exp_f32_e32 v130, v130
	v_exp_f32_e32 v135, v135
	v_rcp_f32_e32 v167, v131
	v_mul_f32_e32 v139, 0xbfb8aa3b, v124
	v_add_f32_e32 v130, 1.0, v130
	v_rcp_f32_e32 v137, v130
	v_pk_add_f32 v[130:131], v[134:135], 1.0 op_sel_hi:[1,0]
	v_min_f32_e32 v139, 0x42700000, v139
	v_rcp_f32_e32 v168, v130
	v_pk_mul_f32 v[136:137], v[136:137], v[130:131]
	v_mul_f32_e32 v130, 0xbfb8aa3b, v122
	v_min_f32_e32 v130, 0x42700000, v130
	v_rcp_f32_e32 v169, v131
	v_exp_f32_e32 v131, v130
	v_exp_f32_e32 v139, v139
	v_mul_f32_e32 v130, 0xbfb8aa3b, v114
	v_min_f32_e32 v130, 0x42700000, v130
	v_add_f32_e32 v134, 1.0, v131
	v_mul_f32_e32 v131, 0xbfb8aa3b, v123
	v_add_f32_e32 v139, 1.0, v139
	v_min_f32_e32 v131, 0x42700000, v131
	v_rcp_f32_e32 v142, v139
	v_mul_f32_e32 v139, 0xbfb8aa3b, v125
	v_exp_f32_e32 v135, v131
	v_min_f32_e32 v139, 0x42700000, v139
	v_exp_f32_e32 v139, v139
	v_mul_f32_e32 v131, 0xbfb8aa3b, v115
	v_min_f32_e32 v131, 0x42700000, v131
	v_mul_f32_e32 v140, 0xbfb8aa3b, v116
	v_mul_f32_e32 v141, 0xbfb8aa3b, v117
	v_exp_f32_e32 v130, v130
	v_exp_f32_e32 v131, v131
	v_add_f32_e32 v135, 1.0, v135
	v_min_f32_e32 v140, 0x42700000, v140
	v_min_f32_e32 v141, 0x42700000, v141
	v_rcp_f32_e32 v134, v134
	v_rcp_f32_e32 v135, v135
	v_exp_f32_e32 v140, v140
	v_exp_f32_e32 v141, v141
	v_add_f32_e32 v139, 1.0, v139
	v_rcp_f32_e32 v143, v139
	v_pk_add_f32 v[130:131], v[130:131], 1.0 op_sel_hi:[1,0]
	s_lshl_b32 s11, s10, 7
	v_rcp_f32_e32 v170, v130
	v_pk_mul_f32 v[144:145], v[134:135], v[130:131]
	v_rcp_f32_e32 v171, v131
	v_pk_add_f32 v[130:131], v[140:141], 1.0 op_sel_hi:[1,0]
	v_cvt_pk_bf16_f32 v134, v132, v133
	v_add_u32_e32 v132, s1, v166
	v_pk_mul_f32 v[140:141], v[142:143], v[130:131]
	v_ashrrev_i32_e32 v133, 31, v132
	v_cvt_pk_bf16_f32 v135, v136, v137
	v_cvt_pk_bf16_f32 v137, v140, v141
	v_lshlrev_b64 v[140:141], 11, v[132:133]
	v_mul_f32_e32 v133, 0xbfb8aa3b, v110
	v_min_f32_e32 v133, 0x42700000, v133
	v_exp_f32_e32 v133, v133
	v_lshlrev_b32_e32 v138, 3, v200
	v_readlane_b32 s18, v236, 22
	v_ashrrev_i32_e32 v139, 31, v138
	s_or_b32 s22, s18, s11
	v_rcp_f32_e32 v172, v130
	v_rcp_f32_e32 v173, v131
	v_lshl_add_u64 v[130:131], s[22:23], 0, v[138:139]
	v_lshl_add_u64 v[142:143], s[68:69], 0, v[140:141]
	v_lshlrev_b64 v[130:131], 1, v[130:131]
	v_add_f32_e32 v133, 1.0, v133
	v_lshl_add_u64 v[138:139], v[142:143], 0, v[130:131]
	v_rcp_f32_e32 v142, v133
	v_mul_f32_e32 v133, 0xbfb8aa3b, v111
	v_min_f32_e32 v133, 0x42700000, v133
	v_exp_f32_e32 v133, v133
	v_cvt_pk_bf16_f32 v136, v144, v145
	global_store_dwordx4 v[138:139], v[134:137], off offset:-4096 nt
	v_lshl_add_u64 v[138:139], s[70:71], 0, v[140:141]
	v_add_f32_e32 v133, 1.0, v133
	v_rcp_f32_e32 v143, v133
	v_mul_f32_e32 v133, 0xbfb8aa3b, v112
	v_mul_f32_e32 v140, 0xbfb8aa3b, v102
	v_mul_f32_e32 v141, 0xbfb8aa3b, v103
	v_min_f32_e32 v133, 0x42700000, v133
	v_min_f32_e32 v140, 0x42700000, v140
	v_min_f32_e32 v141, 0x42700000, v141
	v_exp_f32_e32 v133, v133
	v_exp_f32_e32 v140, v140
	v_exp_f32_e32 v141, v141
	v_cvt_pk_bf16_f32 v134, v154, v167
	v_cvt_pk_bf16_f32 v135, v168, v169
	v_cvt_pk_bf16_f32 v136, v170, v171
	v_cvt_pk_bf16_f32 v137, v172, v173
	v_lshl_add_u64 v[138:139], v[138:139], 0, v[130:131]
	v_add_f32_e32 v133, 1.0, v133
	global_store_dwordx4 v[138:139], v[134:137], off offset:-4096 nt
	v_mul_f32_e32 v138, 0xbfb8aa3b, v104
	v_mul_f32_e32 v139, 0xbfb8aa3b, v105
	v_pk_add_f32 v[134:135], v[140:141], 1.0 op_sel_hi:[1,0]
	v_rcp_f32_e32 v140, v133
	v_mul_f32_e32 v133, 0xbfb8aa3b, v113
	v_min_f32_e32 v133, 0x42700000, v133
	v_exp_f32_e32 v133, v133
	v_min_f32_e32 v138, 0x42700000, v138
	v_min_f32_e32 v139, 0x42700000, v139
	v_exp_f32_e32 v138, v138
	v_exp_f32_e32 v139, v139
	v_add_f32_e32 v133, 1.0, v133
	v_rcp_f32_e32 v141, v133
	v_pk_mul_f32 v[136:137], v[142:143], v[134:135]
	v_rcp_f32_e32 v133, v134
	v_rcp_f32_e32 v154, v135
	v_pk_add_f32 v[134:135], v[138:139], 1.0 op_sel_hi:[1,0]
	s_mov_b64 s[88:89], 0
	v_pk_mul_f32 v[138:139], v[140:141], v[134:135]
	v_mul_f32_e32 v140, 0xbfb8aa3b, v106
	v_min_f32_e32 v140, 0x42700000, v140
	v_exp_f32_e32 v141, v140
	v_mul_f32_e32 v140, 0xbfb8aa3b, v98
	v_min_f32_e32 v140, 0x42700000, v140
	v_exp_f32_e32 v140, v140
	v_add_f32_e32 v141, 1.0, v141
; __device__ __forceinline__ unsigned long long rt() { return __builtin_amdgcn_s_memrealtime(); }
; __device__ __forceinline__ u32x4 pack8f(const f32x4 a, const f32x4 b) { u32x4 w; w.x = cvt_pk_bf16(a[0], a[1]); w.y = cvt_pk_bf16(a[2], a[3]); w.z = cvt_pk_bf16(b[0], b[1]); w.w = cvt_pk_bf16(b[2], b[3]); return w; }
;     __device__ __forceinline__ void operator()(f32x4 (&acc)[2][2][4][2], const Unit& u, int wr, int wc, int fr, int fq) const {
;     ...
;                     f32x4 rt[2], s1[2];
; #pragma unroll
;                     for (int n = 0; n < 2; ++n)
; #pragma unroll
;                         for (int i = 0; i < 4; ++i) {
;                             const float e0 = __builtin_amdgcn_exp2f(fminf(-1.4426950408889634f * acc[ai][0][m][n][i], 60.f)), e1 = __builtin_amdgcn_exp2f(fminf(-1.4426950408889634f * acc[ai][1][m][n][i], 60.f));
;                             rt[n][i] = (1.f + e1) * __builtin_amdgcn_rcpf(1.f + e0); s1[n][i] = __builtin_amdgcn_rcpf(1.f + e1); }
;                     __builtin_nontemporal_store(pack8f(rt[0], rt[1]), (u32x4*)(RT + (size_t)(u.pm * 256 + rl) * DM + j0));
;                     __builtin_nontemporal_store(pack8f(s1[0], s1[1]), (u32x4*)(G1 + (size_t)(u.pm * 256 + rl) * DM + j0));
	v_rcp_f32_e32 v142, v141
	v_mul_f32_e32 v141, 0xbfb8aa3b, v107
	v_min_f32_e32 v141, 0x42700000, v141
	v_exp_f32_e32 v143, v141
	v_mul_f32_e32 v141, 0xbfb8aa3b, v99
	v_min_f32_e32 v141, 0x42700000, v141
	v_exp_f32_e32 v141, v141
	v_add_f32_e32 v143, 1.0, v143
	v_rcp_f32_e32 v143, v143
	v_rcp_f32_e32 v167, v134
	v_rcp_f32_e32 v168, v135
	v_pk_add_f32 v[134:135], v[140:141], 1.0 op_sel_hi:[1,0]
	s_nop 0
	v_pk_mul_f32 v[140:141], v[142:143], v[134:135]
	v_mul_f32_e32 v142, 0xbfb8aa3b, v108
	v_min_f32_e32 v142, 0x42700000, v142
	v_exp_f32_e32 v143, v142
	v_mul_f32_e32 v142, 0xbfb8aa3b, v100
	v_min_f32_e32 v142, 0x42700000, v142
	v_exp_f32_e32 v142, v142
	v_add_f32_e32 v143, 1.0, v143
	v_rcp_f32_e32 v144, v143
	v_mul_f32_e32 v143, 0xbfb8aa3b, v109
	v_min_f32_e32 v143, 0x42700000, v143
	v_exp_f32_e32 v145, v143
	v_mul_f32_e32 v143, 0xbfb8aa3b, v101
	v_min_f32_e32 v143, 0x42700000, v143
	v_exp_f32_e32 v143, v143
	v_add_f32_e32 v145, 1.0, v145
	v_rcp_f32_e32 v145, v145
	v_rcp_f32_e32 v169, v134
	v_rcp_f32_e32 v170, v135
	v_pk_add_f32 v[134:135], v[142:143], 1.0 op_sel_hi:[1,0]
	s_nop 0
	v_pk_mul_f32 v[142:143], v[144:145], v[134:135]
	v_rcp_f32_e32 v145, v135
	v_cvt_pk_bf16_f32 v135, v138, v139
	v_add_u32_e32 v138, 16, v132
	v_ashrrev_i32_e32 v139, 31, v138
	v_lshlrev_b64 v[138:139], 11, v[138:139]
	v_rcp_f32_e32 v144, v134
	v_cvt_pk_bf16_f32 v134, v136, v137
	v_cvt_pk_bf16_f32 v136, v140, v141
	v_lshl_add_u64 v[140:141], s[68:69], 0, v[138:139]
	v_cvt_pk_bf16_f32 v137, v142, v143
	v_lshl_add_u64 v[140:141], v[140:141], 0, v[130:131]
	global_store_dwordx4 v[140:141], v[134:137], off offset:-4096 nt
	v_mul_f32_e32 v140, 0xbfb8aa3b, v86
	v_mul_f32_e32 v141, 0xbfb8aa3b, v87
	v_cvt_pk_bf16_f32 v134, v133, v154
	v_mul_f32_e32 v133, 0xbfb8aa3b, v94
	v_min_f32_e32 v133, 0x42700000, v133
	v_exp_f32_e32 v133, v133
	v_min_f32_e32 v140, 0x42700000, v140
	v_min_f32_e32 v141, 0x42700000, v141
	v_exp_f32_e32 v140, v140
	v_add_f32_e32 v133, 1.0, v133
	v_rcp_f32_e32 v142, v133
	v_mul_f32_e32 v133, 0xbfb8aa3b, v95
	v_min_f32_e32 v133, 0x42700000, v133
	v_exp_f32_e32 v133, v133
	v_exp_f32_e32 v141, v141
	v_lshl_add_u64 v[138:139], s[70:71], 0, v[138:139]
	v_cvt_pk_bf16_f32 v135, v167, v168
	v_add_f32_e32 v133, 1.0, v133
	v_rcp_f32_e32 v143, v133
	v_mul_f32_e32 v133, 0xbfb8aa3b, v96
	v_min_f32_e32 v133, 0x42700000, v133
	v_exp_f32_e32 v133, v133
	v_cvt_pk_bf16_f32 v136, v169, v170
	v_cvt_pk_bf16_f32 v137, v144, v145
	v_lshl_add_u64 v[138:139], v[138:139], 0, v[130:131]
	v_add_f32_e32 v133, 1.0, v133
	global_store_dwordx4 v[138:139], v[134:137], off offset:-4096 nt
	v_mul_f32_e32 v138, 0xbfb8aa3b, v88
	v_mul_f32_e32 v139, 0xbfb8aa3b, v89
	v_pk_add_f32 v[134:135], v[140:141], 1.0 op_sel_hi:[1,0]
	v_rcp_f32_e32 v140, v133
	v_mul_f32_e32 v133, 0xbfb8aa3b, v97
	v_min_f32_e32 v133, 0x42700000, v133
	v_exp_f32_e32 v133, v133
	v_min_f32_e32 v138, 0x42700000, v138
	v_min_f32_e32 v139, 0x42700000, v139
	v_exp_f32_e32 v138, v138
	v_exp_f32_e32 v139, v139
	v_add_f32_e32 v133, 1.0, v133
	v_rcp_f32_e32 v141, v133
	v_pk_mul_f32 v[136:137], v[142:143], v[134:135]
	v_rcp_f32_e32 v133, v134
	v_rcp_f32_e32 v154, v135
	v_pk_add_f32 v[134:135], v[138:139], 1.0 op_sel_hi:[1,0]
	s_nop 0
	v_pk_mul_f32 v[138:139], v[140:141], v[134:135]
	v_mul_f32_e32 v140, 0xbfb8aa3b, v90
	v_min_f32_e32 v140, 0x42700000, v140
	v_exp_f32_e32 v141, v140
	v_mul_f32_e32 v140, 0xbfb8aa3b, v82
	v_min_f32_e32 v140, 0x42700000, v140
	v_exp_f32_e32 v140, v140
	v_add_f32_e32 v141, 1.0, v141
	v_rcp_f32_e32 v142, v141
	v_mul_f32_e32 v141, 0xbfb8aa3b, v91
	v_min_f32_e32 v141, 0x42700000, v141
	v_exp_f32_e32 v143, v141
	v_mul_f32_e32 v141, 0xbfb8aa3b, v83
	v_min_f32_e32 v141, 0x42700000, v141
	v_exp_f32_e32 v141, v141
	v_add_f32_e32 v143, 1.0, v143
	v_rcp_f32_e32 v143, v143
	v_rcp_f32_e32 v167, v134
	v_rcp_f32_e32 v168, v135
	v_pk_add_f32 v[134:135], v[140:141], 1.0 op_sel_hi:[1,0]
	s_nop 0
	v_pk_mul_f32 v[140:141], v[142:143], v[134:135]
	v_mul_f32_e32 v142, 0xbfb8aa3b, v92
	v_min_f32_e32 v142, 0x42700000, v142
	v_exp_f32_e32 v143, v142
	v_mul_f32_e32 v142, 0xbfb8aa3b, v84
	v_min_f32_e32 v142, 0x42700000, v142
	v_exp_f32_e32 v142, v142
	v_add_f32_e32 v143, 1.0, v143
	v_rcp_f32_e32 v144, v143
	v_mul_f32_e32 v143, 0xbfb8aa3b, v93
	v_min_f32_e32 v143, 0x42700000, v143
	v_exp_f32_e32 v145, v143
	v_mul_f32_e32 v143, 0xbfb8aa3b, v85
	v_min_f32_e32 v143, 0x42700000, v143
	v_exp_f32_e32 v143, v143
	v_add_f32_e32 v145, 1.0, v145
	v_rcp_f32_e32 v145, v145
	v_rcp_f32_e32 v169, v134
	v_rcp_f32_e32 v170, v135
	v_pk_add_f32 v[134:135], v[142:143], 1.0 op_sel_hi:[1,0]
	s_nop 0
	v_pk_mul_f32 v[142:143], v[144:145], v[134:135]
	v_rcp_f32_e32 v145, v135
	v_cvt_pk_bf16_f32 v135, v138, v139
	v_add_u32_e32 v138, 32, v132
	v_ashrrev_i32_e32 v139, 31, v138
	v_lshlrev_b64 v[138:139], 11, v[138:139]
	v_rcp_f32_e32 v144, v134
	v_cvt_pk_bf16_f32 v134, v136, v137
	v_cvt_pk_bf16_f32 v136, v140, v141
	v_lshl_add_u64 v[140:141], s[68:69], 0, v[138:139]
	v_cvt_pk_bf16_f32 v137, v142, v143
	v_lshl_add_u64 v[140:141], v[140:141], 0, v[130:131]
	global_store_dwordx4 v[140:141], v[134:137], off offset:-4096 nt
	v_mul_f32_e32 v140, 0xbfb8aa3b, v70
	v_mul_f32_e32 v141, 0xbfb8aa3b, v71
	v_cvt_pk_bf16_f32 v134, v133, v154
	v_mul_f32_e32 v133, 0xbfb8aa3b, v78
	v_min_f32_e32 v133, 0x42700000, v133
	v_exp_f32_e32 v133, v133
	v_min_f32_e32 v140, 0x42700000, v140
	v_min_f32_e32 v141, 0x42700000, v141
	v_exp_f32_e32 v140, v140
	v_add_f32_e32 v133, 1.0, v133
	v_rcp_f32_e32 v142, v133
	v_mul_f32_e32 v133, 0xbfb8aa3b, v79
	v_min_f32_e32 v133, 0x42700000, v133
	v_exp_f32_e32 v133, v133
	v_exp_f32_e32 v141, v141
	v_lshl_add_u64 v[138:139], s[70:71], 0, v[138:139]
; __device__ __forceinline__ unsigned long long rt() { return __builtin_amdgcn_s_memrealtime(); }
; __device__ __forceinline__ u32x4 pack8f(const f32x4 a, const f32x4 b) { u32x4 w; w.x = cvt_pk_bf16(a[0], a[1]); w.y = cvt_pk_bf16(a[2], a[3]); w.z = cvt_pk_bf16(b[0], b[1]); w.w = cvt_pk_bf16(b[2], b[3]); return w; }
;     __device__ __forceinline__ void operator()(f32x4 (&acc)[2][2][4][2], const Unit& u, int wr, int wc, int fr, int fq) const {
;     ...
;                     f32x4 rt[2], s1[2];
; #pragma unroll
;                     for (int n = 0; n < 2; ++n)
; #pragma unroll
;                         for (int i = 0; i < 4; ++i) {
;                             const float e0 = __builtin_amdgcn_exp2f(fminf(-1.4426950408889634f * acc[ai][0][m][n][i], 60.f)), e1 = __builtin_amdgcn_exp2f(fminf(-1.4426950408889634f * acc[ai][1][m][n][i], 60.f));
;                             rt[n][i] = (1.f + e1) * __builtin_amdgcn_rcpf(1.f + e0); s1[n][i] = __builtin_amdgcn_rcpf(1.f + e1); }
;                     __builtin_nontemporal_store(pack8f(rt[0], rt[1]), (u32x4*)(RT + (size_t)(u.pm * 256 + rl) * DM + j0));
;                     __builtin_nontemporal_store(pack8f(s1[0], s1[1]), (u32x4*)(G1 + (size_t)(u.pm * 256 + rl) * DM + j0));
	v_cvt_pk_bf16_f32 v135, v167, v168
	v_add_f32_e32 v133, 1.0, v133
	v_rcp_f32_e32 v143, v133
	v_mul_f32_e32 v133, 0xbfb8aa3b, v80
	v_min_f32_e32 v133, 0x42700000, v133
	v_exp_f32_e32 v133, v133
	v_cvt_pk_bf16_f32 v136, v169, v170
	v_cvt_pk_bf16_f32 v137, v144, v145
	v_lshl_add_u64 v[138:139], v[138:139], 0, v[130:131]
	v_add_f32_e32 v133, 1.0, v133
	global_store_dwordx4 v[138:139], v[134:137], off offset:-4096 nt
	v_mul_f32_e32 v138, 0xbfb8aa3b, v72
	v_mul_f32_e32 v139, 0xbfb8aa3b, v73
	v_pk_add_f32 v[134:135], v[140:141], 1.0 op_sel_hi:[1,0]
	v_rcp_f32_e32 v140, v133
	v_mul_f32_e32 v133, 0xbfb8aa3b, v81
	v_min_f32_e32 v133, 0x42700000, v133
	v_exp_f32_e32 v133, v133
	v_min_f32_e32 v138, 0x42700000, v138
	v_min_f32_e32 v139, 0x42700000, v139
	v_exp_f32_e32 v138, v138
	v_exp_f32_e32 v139, v139
	v_add_f32_e32 v133, 1.0, v133
	v_rcp_f32_e32 v141, v133
	v_pk_mul_f32 v[136:137], v[142:143], v[134:135]
	v_rcp_f32_e32 v133, v134
	v_rcp_f32_e32 v154, v135
	v_pk_add_f32 v[134:135], v[138:139], 1.0 op_sel_hi:[1,0]
	s_nop 0
	v_pk_mul_f32 v[138:139], v[140:141], v[134:135]
	v_mul_f32_e32 v140, 0xbfb8aa3b, v74
	v_min_f32_e32 v140, 0x42700000, v140
	v_exp_f32_e32 v141, v140
	v_mul_f32_e32 v140, 0xbfb8aa3b, v66
	v_min_f32_e32 v140, 0x42700000, v140
	v_exp_f32_e32 v140, v140
	v_add_f32_e32 v141, 1.0, v141
	v_rcp_f32_e32 v142, v141
	v_mul_f32_e32 v141, 0xbfb8aa3b, v75
	v_min_f32_e32 v141, 0x42700000, v141
	v_exp_f32_e32 v143, v141
	v_mul_f32_e32 v141, 0xbfb8aa3b, v67
	v_min_f32_e32 v141, 0x42700000, v141
	v_exp_f32_e32 v141, v141
	v_add_f32_e32 v143, 1.0, v143
	v_rcp_f32_e32 v143, v143
	v_rcp_f32_e32 v167, v134
	v_rcp_f32_e32 v168, v135
	v_pk_add_f32 v[134:135], v[140:141], 1.0 op_sel_hi:[1,0]
	s_nop 0
	v_pk_mul_f32 v[140:141], v[142:143], v[134:135]
	v_mul_f32_e32 v142, 0xbfb8aa3b, v76
	v_min_f32_e32 v142, 0x42700000, v142
	v_exp_f32_e32 v143, v142
	v_mul_f32_e32 v142, 0xbfb8aa3b, v68
	v_min_f32_e32 v142, 0x42700000, v142
	v_exp_f32_e32 v142, v142
	v_add_f32_e32 v143, 1.0, v143
	v_rcp_f32_e32 v144, v143
	v_mul_f32_e32 v143, 0xbfb8aa3b, v77
	v_min_f32_e32 v143, 0x42700000, v143
	v_exp_f32_e32 v145, v143
	v_mul_f32_e32 v143, 0xbfb8aa3b, v69
	v_min_f32_e32 v143, 0x42700000, v143
	v_exp_f32_e32 v143, v143
	v_add_f32_e32 v145, 1.0, v145
	v_rcp_f32_e32 v145, v145
	v_rcp_f32_e32 v169, v134
	v_rcp_f32_e32 v170, v135
	v_pk_add_f32 v[134:135], v[142:143], 1.0 op_sel_hi:[1,0]
	s_nop 0
	v_pk_mul_f32 v[142:143], v[144:145], v[134:135]
	v_rcp_f32_e32 v145, v135
	v_cvt_pk_bf16_f32 v135, v138, v139
	v_add_u32_e32 v138, 48, v132
	v_ashrrev_i32_e32 v139, 31, v138
	v_lshlrev_b64 v[138:139], 11, v[138:139]
	v_rcp_f32_e32 v144, v134
	v_cvt_pk_bf16_f32 v134, v136, v137
	v_cvt_pk_bf16_f32 v136, v140, v141
	v_lshl_add_u64 v[140:141], s[68:69], 0, v[138:139]
	v_cvt_pk_bf16_f32 v137, v142, v143
	v_lshl_add_u64 v[140:141], v[140:141], 0, v[130:131]
	global_store_dwordx4 v[140:141], v[134:137], off offset:-4096 nt
	v_mul_f32_e32 v140, 0xbfb8aa3b, v54
	v_mul_f32_e32 v141, 0xbfb8aa3b, v55
	v_cvt_pk_bf16_f32 v134, v133, v154
	v_mul_f32_e32 v133, 0xbfb8aa3b, v62
	v_min_f32_e32 v133, 0x42700000, v133
	v_exp_f32_e32 v133, v133
	v_min_f32_e32 v140, 0x42700000, v140
	v_min_f32_e32 v141, 0x42700000, v141
	v_exp_f32_e32 v140, v140
	v_add_f32_e32 v133, 1.0, v133
	v_rcp_f32_e32 v142, v133
	v_mul_f32_e32 v133, 0xbfb8aa3b, v63
	v_min_f32_e32 v133, 0x42700000, v133
	v_exp_f32_e32 v133, v133
	v_exp_f32_e32 v141, v141
	v_lshl_add_u64 v[138:139], s[70:71], 0, v[138:139]
	v_cvt_pk_bf16_f32 v135, v167, v168
	v_add_f32_e32 v133, 1.0, v133
	v_rcp_f32_e32 v143, v133
	v_mul_f32_e32 v133, 0xbfb8aa3b, v64
	v_min_f32_e32 v133, 0x42700000, v133
	v_exp_f32_e32 v133, v133
	v_cvt_pk_bf16_f32 v136, v169, v170
	v_cvt_pk_bf16_f32 v137, v144, v145
	v_lshl_add_u64 v[138:139], v[138:139], 0, v[130:131]
	v_add_f32_e32 v133, 1.0, v133
	global_store_dwordx4 v[138:139], v[134:137], off offset:-4096 nt
	v_mul_f32_e32 v138, 0xbfb8aa3b, v56
	v_mul_f32_e32 v139, 0xbfb8aa3b, v57
	v_pk_add_f32 v[134:135], v[140:141], 1.0 op_sel_hi:[1,0]
	v_rcp_f32_e32 v140, v133
	v_mul_f32_e32 v133, 0xbfb8aa3b, v65
	v_min_f32_e32 v133, 0x42700000, v133
	v_exp_f32_e32 v133, v133
	v_min_f32_e32 v138, 0x42700000, v138
	v_min_f32_e32 v139, 0x42700000, v139
	v_exp_f32_e32 v138, v138
	v_exp_f32_e32 v139, v139
	v_add_f32_e32 v133, 1.0, v133
	v_rcp_f32_e32 v141, v133
	v_pk_mul_f32 v[136:137], v[142:143], v[134:135]
	v_rcp_f32_e32 v133, v134
	v_rcp_f32_e32 v154, v135
	v_pk_add_f32 v[134:135], v[138:139], 1.0 op_sel_hi:[1,0]
	s_nop 0
	v_pk_mul_f32 v[138:139], v[140:141], v[134:135]
	v_mul_f32_e32 v140, 0xbfb8aa3b, v58
	v_min_f32_e32 v140, 0x42700000, v140
	v_exp_f32_e32 v141, v140
	v_mul_f32_e32 v140, 0xbfb8aa3b, v50
	v_min_f32_e32 v140, 0x42700000, v140
	v_exp_f32_e32 v140, v140
	v_add_f32_e32 v141, 1.0, v141
	v_rcp_f32_e32 v142, v141
	v_mul_f32_e32 v141, 0xbfb8aa3b, v59
	v_min_f32_e32 v141, 0x42700000, v141
	v_exp_f32_e32 v143, v141
	v_mul_f32_e32 v141, 0xbfb8aa3b, v51
	v_min_f32_e32 v141, 0x42700000, v141
	v_exp_f32_e32 v141, v141
	v_add_f32_e32 v143, 1.0, v143
	v_rcp_f32_e32 v143, v143
	v_rcp_f32_e32 v167, v134
	v_rcp_f32_e32 v168, v135
	v_pk_add_f32 v[134:135], v[140:141], 1.0 op_sel_hi:[1,0]
	s_nop 0
	v_pk_mul_f32 v[140:141], v[142:143], v[134:135]
	v_mul_f32_e32 v142, 0xbfb8aa3b, v60
	v_min_f32_e32 v142, 0x42700000, v142
	v_exp_f32_e32 v143, v142
	v_mul_f32_e32 v142, 0xbfb8aa3b, v52
	v_min_f32_e32 v142, 0x42700000, v142
	v_exp_f32_e32 v142, v142
	v_add_f32_e32 v143, 1.0, v143
	v_rcp_f32_e32 v144, v143
	v_mul_f32_e32 v143, 0xbfb8aa3b, v61
	v_min_f32_e32 v143, 0x42700000, v143
	v_exp_f32_e32 v145, v143
	v_mul_f32_e32 v143, 0xbfb8aa3b, v53
; __device__ __forceinline__ unsigned long long rt() { return __builtin_amdgcn_s_memrealtime(); }
; __device__ __forceinline__ u32x4 pack8f(const f32x4 a, const f32x4 b) { u32x4 w; w.x = cvt_pk_bf16(a[0], a[1]); w.y = cvt_pk_bf16(a[2], a[3]); w.z = cvt_pk_bf16(b[0], b[1]); w.w = cvt_pk_bf16(b[2], b[3]); return w; }
;     __device__ __forceinline__ void operator()(f32x4 (&acc)[2][2][4][2], const Unit& u, int wr, int wc, int fr, int fq) const {
;     ...
;                     f32x4 rt[2], s1[2];
; #pragma unroll
;                     for (int n = 0; n < 2; ++n)
; #pragma unroll
;                         for (int i = 0; i < 4; ++i) {
;                             const float e0 = __builtin_amdgcn_exp2f(fminf(-1.4426950408889634f * acc[ai][0][m][n][i], 60.f)), e1 = __builtin_amdgcn_exp2f(fminf(-1.4426950408889634f * acc[ai][1][m][n][i], 60.f));
;                             rt[n][i] = (1.f + e1) * __builtin_amdgcn_rcpf(1.f + e0); s1[n][i] = __builtin_amdgcn_rcpf(1.f + e1); }
;                     __builtin_nontemporal_store(pack8f(rt[0], rt[1]), (u32x4*)(RT + (size_t)(u.pm * 256 + rl) * DM + j0));
;                     __builtin_nontemporal_store(pack8f(s1[0], s1[1]), (u32x4*)(G1 + (size_t)(u.pm * 256 + rl) * DM + j0));
	v_min_f32_e32 v143, 0x42700000, v143
	v_exp_f32_e32 v143, v143
	v_add_f32_e32 v145, 1.0, v145
	v_rcp_f32_e32 v145, v145
	v_rcp_f32_e32 v169, v134
	v_rcp_f32_e32 v170, v135
	v_pk_add_f32 v[134:135], v[142:143], 1.0 op_sel_hi:[1,0]
	s_nop 0
	v_pk_mul_f32 v[142:143], v[144:145], v[134:135]
	v_rcp_f32_e32 v145, v135
	v_cvt_pk_bf16_f32 v135, v138, v139
	v_add_u32_e32 v138, 0x80, v132
	v_ashrrev_i32_e32 v139, 31, v138
	v_lshlrev_b64 v[138:139], 11, v[138:139]
	v_rcp_f32_e32 v144, v134
	v_cvt_pk_bf16_f32 v134, v136, v137
	v_cvt_pk_bf16_f32 v136, v140, v141
	v_lshl_add_u64 v[140:141], s[68:69], 0, v[138:139]
	v_cvt_pk_bf16_f32 v137, v142, v143
	v_lshl_add_u64 v[140:141], v[140:141], 0, v[130:131]
	global_store_dwordx4 v[140:141], v[134:137], off offset:-4096 nt
	v_mul_f32_e32 v140, 0xbfb8aa3b, v38
	v_mul_f32_e32 v141, 0xbfb8aa3b, v39
	v_cvt_pk_bf16_f32 v134, v133, v154
	v_mul_f32_e32 v133, 0xbfb8aa3b, v46
	v_min_f32_e32 v133, 0x42700000, v133
	v_exp_f32_e32 v133, v133
	v_min_f32_e32 v140, 0x42700000, v140
	v_min_f32_e32 v141, 0x42700000, v141
	v_exp_f32_e32 v140, v140
	v_add_f32_e32 v133, 1.0, v133
	v_rcp_f32_e32 v142, v133
	v_mul_f32_e32 v133, 0xbfb8aa3b, v47
	v_min_f32_e32 v133, 0x42700000, v133
	v_exp_f32_e32 v133, v133
	v_exp_f32_e32 v141, v141
	v_lshl_add_u64 v[138:139], s[70:71], 0, v[138:139]
	v_cvt_pk_bf16_f32 v135, v167, v168
	v_add_f32_e32 v133, 1.0, v133
	v_rcp_f32_e32 v143, v133
	v_mul_f32_e32 v133, 0xbfb8aa3b, v48
	v_min_f32_e32 v133, 0x42700000, v133
	v_exp_f32_e32 v133, v133
	v_cvt_pk_bf16_f32 v136, v169, v170
	v_cvt_pk_bf16_f32 v137, v144, v145
	v_lshl_add_u64 v[138:139], v[138:139], 0, v[130:131]
	v_add_f32_e32 v133, 1.0, v133
	global_store_dwordx4 v[138:139], v[134:137], off offset:-4096 nt
	v_mul_f32_e32 v138, 0xbfb8aa3b, v40
	v_mul_f32_e32 v139, 0xbfb8aa3b, v41
	v_pk_add_f32 v[134:135], v[140:141], 1.0 op_sel_hi:[1,0]
	v_rcp_f32_e32 v140, v133
	v_mul_f32_e32 v133, 0xbfb8aa3b, v49
	v_min_f32_e32 v133, 0x42700000, v133
	v_exp_f32_e32 v133, v133
	v_min_f32_e32 v138, 0x42700000, v138
	v_min_f32_e32 v139, 0x42700000, v139
	v_exp_f32_e32 v138, v138
	v_exp_f32_e32 v139, v139
	v_add_f32_e32 v133, 1.0, v133
	v_rcp_f32_e32 v141, v133
	v_pk_mul_f32 v[136:137], v[142:143], v[134:135]
	v_rcp_f32_e32 v133, v134
	v_rcp_f32_e32 v154, v135
	v_pk_add_f32 v[134:135], v[138:139], 1.0 op_sel_hi:[1,0]
	s_nop 0
	v_pk_mul_f32 v[138:139], v[140:141], v[134:135]
	v_mul_f32_e32 v140, 0xbfb8aa3b, v42
	v_min_f32_e32 v140, 0x42700000, v140
	v_exp_f32_e32 v141, v140
	v_mul_f32_e32 v140, 0xbfb8aa3b, v34
	v_min_f32_e32 v140, 0x42700000, v140
	v_exp_f32_e32 v140, v140
	v_add_f32_e32 v141, 1.0, v141
	v_rcp_f32_e32 v142, v141
	v_mul_f32_e32 v141, 0xbfb8aa3b, v43
	v_min_f32_e32 v141, 0x42700000, v141
	v_exp_f32_e32 v143, v141
	v_mul_f32_e32 v141, 0xbfb8aa3b, v35
	v_min_f32_e32 v141, 0x42700000, v141
	v_exp_f32_e32 v141, v141
	v_add_f32_e32 v143, 1.0, v143
	v_rcp_f32_e32 v143, v143
	v_rcp_f32_e32 v167, v134
	v_rcp_f32_e32 v168, v135
	v_pk_add_f32 v[134:135], v[140:141], 1.0 op_sel_hi:[1,0]
	s_nop 0
	v_pk_mul_f32 v[140:141], v[142:143], v[134:135]
	v_mul_f32_e32 v142, 0xbfb8aa3b, v44
	v_min_f32_e32 v142, 0x42700000, v142
	v_exp_f32_e32 v143, v142
	v_mul_f32_e32 v142, 0xbfb8aa3b, v36
	v_min_f32_e32 v142, 0x42700000, v142
	v_exp_f32_e32 v142, v142
	v_add_f32_e32 v143, 1.0, v143
	v_rcp_f32_e32 v144, v143
	v_mul_f32_e32 v143, 0xbfb8aa3b, v45
	v_min_f32_e32 v143, 0x42700000, v143
	v_exp_f32_e32 v145, v143
	v_mul_f32_e32 v143, 0xbfb8aa3b, v37
	v_min_f32_e32 v143, 0x42700000, v143
	v_exp_f32_e32 v143, v143
	v_add_f32_e32 v145, 1.0, v145
	v_rcp_f32_e32 v145, v145
	v_rcp_f32_e32 v169, v134
	v_rcp_f32_e32 v170, v135
	v_pk_add_f32 v[134:135], v[142:143], 1.0 op_sel_hi:[1,0]
	s_nop 0
	v_pk_mul_f32 v[142:143], v[144:145], v[134:135]
	v_rcp_f32_e32 v145, v135
	v_cvt_pk_bf16_f32 v135, v138, v139
	v_add_u32_e32 v138, 0x90, v132
	v_ashrrev_i32_e32 v139, 31, v138
	v_lshlrev_b64 v[138:139], 11, v[138:139]
	v_rcp_f32_e32 v144, v134
	v_cvt_pk_bf16_f32 v134, v136, v137
	v_cvt_pk_bf16_f32 v136, v140, v141
	v_lshl_add_u64 v[140:141], s[68:69], 0, v[138:139]
	v_cvt_pk_bf16_f32 v137, v142, v143
	v_lshl_add_u64 v[140:141], v[140:141], 0, v[130:131]
	global_store_dwordx4 v[140:141], v[134:137], off offset:-4096 nt
	v_mul_f32_e32 v140, 0xbfb8aa3b, v22
	v_mul_f32_e32 v141, 0xbfb8aa3b, v23
	v_cvt_pk_bf16_f32 v134, v133, v154
	v_mul_f32_e32 v133, 0xbfb8aa3b, v30
	v_min_f32_e32 v133, 0x42700000, v133
	v_exp_f32_e32 v133, v133
	v_min_f32_e32 v140, 0x42700000, v140
	v_min_f32_e32 v141, 0x42700000, v141
	v_exp_f32_e32 v140, v140
	v_add_f32_e32 v133, 1.0, v133
	v_rcp_f32_e32 v142, v133
	v_mul_f32_e32 v133, 0xbfb8aa3b, v31
	v_min_f32_e32 v133, 0x42700000, v133
	v_exp_f32_e32 v133, v133
	v_exp_f32_e32 v141, v141
	v_lshl_add_u64 v[138:139], s[70:71], 0, v[138:139]
	v_cvt_pk_bf16_f32 v135, v167, v168
	v_add_f32_e32 v133, 1.0, v133
	v_rcp_f32_e32 v143, v133
	v_mul_f32_e32 v133, 0xbfb8aa3b, v32
	v_min_f32_e32 v133, 0x42700000, v133
	v_exp_f32_e32 v133, v133
	v_cvt_pk_bf16_f32 v136, v169, v170
	v_cvt_pk_bf16_f32 v137, v144, v145
	v_lshl_add_u64 v[138:139], v[138:139], 0, v[130:131]
	v_add_f32_e32 v133, 1.0, v133
	global_store_dwordx4 v[138:139], v[134:137], off offset:-4096 nt
	v_mul_f32_e32 v138, 0xbfb8aa3b, v24
	v_mul_f32_e32 v139, 0xbfb8aa3b, v25
	v_pk_add_f32 v[134:135], v[140:141], 1.0 op_sel_hi:[1,0]
	v_rcp_f32_e32 v140, v133
	v_mul_f32_e32 v133, 0xbfb8aa3b, v33
	v_min_f32_e32 v133, 0x42700000, v133
	v_exp_f32_e32 v133, v133
	v_min_f32_e32 v138, 0x42700000, v138
	v_min_f32_e32 v139, 0x42700000, v139
	v_exp_f32_e32 v138, v138
	v_exp_f32_e32 v139, v139
	v_add_f32_e32 v133, 1.0, v133
	v_rcp_f32_e32 v141, v133
; __device__ __forceinline__ unsigned long long rt() { return __builtin_amdgcn_s_memrealtime(); }
; __device__ __forceinline__ u32x4 pack8f(const f32x4 a, const f32x4 b) { u32x4 w; w.x = cvt_pk_bf16(a[0], a[1]); w.y = cvt_pk_bf16(a[2], a[3]); w.z = cvt_pk_bf16(b[0], b[1]); w.w = cvt_pk_bf16(b[2], b[3]); return w; }
;     __device__ __forceinline__ void operator()(f32x4 (&acc)[2][2][4][2], const Unit& u, int wr, int wc, int fr, int fq) const {
;     ...
;                     f32x4 rt[2], s1[2];
; #pragma unroll
;                     for (int n = 0; n < 2; ++n)
; #pragma unroll
;                         for (int i = 0; i < 4; ++i) {
;                             const float e0 = __builtin_amdgcn_exp2f(fminf(-1.4426950408889634f * acc[ai][0][m][n][i], 60.f)), e1 = __builtin_amdgcn_exp2f(fminf(-1.4426950408889634f * acc[ai][1][m][n][i], 60.f));
;                             rt[n][i] = (1.f + e1) * __builtin_amdgcn_rcpf(1.f + e0); s1[n][i] = __builtin_amdgcn_rcpf(1.f + e1); }
;                     __builtin_nontemporal_store(pack8f(rt[0], rt[1]), (u32x4*)(RT + (size_t)(u.pm * 256 + rl) * DM + j0));
;                     __builtin_nontemporal_store(pack8f(s1[0], s1[1]), (u32x4*)(G1 + (size_t)(u.pm * 256 + rl) * DM + j0));
	v_pk_mul_f32 v[136:137], v[142:143], v[134:135]
	v_rcp_f32_e32 v133, v134
	v_rcp_f32_e32 v154, v135
	v_pk_add_f32 v[134:135], v[138:139], 1.0 op_sel_hi:[1,0]
	s_nop 0
	v_pk_mul_f32 v[138:139], v[140:141], v[134:135]
	v_mul_f32_e32 v140, 0xbfb8aa3b, v26
	v_min_f32_e32 v140, 0x42700000, v140
	v_exp_f32_e32 v141, v140
	v_mul_f32_e32 v140, 0xbfb8aa3b, v18
	v_min_f32_e32 v140, 0x42700000, v140
	v_exp_f32_e32 v140, v140
	v_add_f32_e32 v141, 1.0, v141
	v_rcp_f32_e32 v142, v141
	v_mul_f32_e32 v141, 0xbfb8aa3b, v27
	v_min_f32_e32 v141, 0x42700000, v141
	v_exp_f32_e32 v143, v141
	v_mul_f32_e32 v141, 0xbfb8aa3b, v19
	v_min_f32_e32 v141, 0x42700000, v141
	v_exp_f32_e32 v141, v141
	v_add_f32_e32 v143, 1.0, v143
	v_rcp_f32_e32 v143, v143
	v_rcp_f32_e32 v167, v134
	v_rcp_f32_e32 v168, v135
	v_pk_add_f32 v[134:135], v[140:141], 1.0 op_sel_hi:[1,0]
	s_nop 0
	v_pk_mul_f32 v[140:141], v[142:143], v[134:135]
	v_mul_f32_e32 v142, 0xbfb8aa3b, v28
	v_min_f32_e32 v142, 0x42700000, v142
	v_exp_f32_e32 v143, v142
	v_mul_f32_e32 v142, 0xbfb8aa3b, v20
	v_min_f32_e32 v142, 0x42700000, v142
	v_exp_f32_e32 v142, v142
	v_add_f32_e32 v143, 1.0, v143
	v_rcp_f32_e32 v144, v143
	v_mul_f32_e32 v143, 0xbfb8aa3b, v29
	v_min_f32_e32 v143, 0x42700000, v143
	v_exp_f32_e32 v145, v143
	v_mul_f32_e32 v143, 0xbfb8aa3b, v21
	v_min_f32_e32 v143, 0x42700000, v143
	v_exp_f32_e32 v143, v143
	v_add_f32_e32 v145, 1.0, v145
	v_rcp_f32_e32 v145, v145
	v_rcp_f32_e32 v169, v134
	v_rcp_f32_e32 v170, v135
	v_pk_add_f32 v[134:135], v[142:143], 1.0 op_sel_hi:[1,0]
	s_nop 0
	v_pk_mul_f32 v[142:143], v[144:145], v[134:135]
	v_rcp_f32_e32 v145, v135
	v_cvt_pk_bf16_f32 v135, v138, v139
	v_add_u32_e32 v138, 0xa0, v132
	v_ashrrev_i32_e32 v139, 31, v138
	v_lshlrev_b64 v[138:139], 11, v[138:139]
	v_rcp_f32_e32 v144, v134
	v_cvt_pk_bf16_f32 v134, v136, v137
	v_cvt_pk_bf16_f32 v136, v140, v141
	v_lshl_add_u64 v[140:141], s[68:69], 0, v[138:139]
	v_cvt_pk_bf16_f32 v137, v142, v143
	v_lshl_add_u64 v[140:141], v[140:141], 0, v[130:131]
	global_store_dwordx4 v[140:141], v[134:137], off offset:-4096 nt
	v_mul_f32_e32 v140, 0xbfb8aa3b, v6
	v_mul_f32_e32 v141, 0xbfb8aa3b, v7
	v_cvt_pk_bf16_f32 v134, v133, v154
	v_mul_f32_e32 v133, 0xbfb8aa3b, v14
	v_min_f32_e32 v133, 0x42700000, v133
	v_exp_f32_e32 v133, v133
	v_min_f32_e32 v140, 0x42700000, v140
	v_min_f32_e32 v141, 0x42700000, v141
	v_exp_f32_e32 v140, v140
	v_add_f32_e32 v133, 1.0, v133
	v_rcp_f32_e32 v142, v133
	v_mul_f32_e32 v133, 0xbfb8aa3b, v15
	v_min_f32_e32 v133, 0x42700000, v133
	v_exp_f32_e32 v133, v133
	v_exp_f32_e32 v141, v141
	v_lshl_add_u64 v[138:139], s[70:71], 0, v[138:139]
	v_cvt_pk_bf16_f32 v135, v167, v168
	v_add_f32_e32 v133, 1.0, v133
	v_rcp_f32_e32 v143, v133
	v_mul_f32_e32 v133, 0xbfb8aa3b, v16
	v_min_f32_e32 v133, 0x42700000, v133
	v_exp_f32_e32 v133, v133
	v_cvt_pk_bf16_f32 v136, v169, v170
	v_cvt_pk_bf16_f32 v137, v144, v145
	v_lshl_add_u64 v[138:139], v[138:139], 0, v[130:131]
	v_add_f32_e32 v133, 1.0, v133
	global_store_dwordx4 v[138:139], v[134:137], off offset:-4096 nt
	v_mul_f32_e32 v138, 0xbfb8aa3b, v8
	v_mul_f32_e32 v139, 0xbfb8aa3b, v9
	v_pk_add_f32 v[134:135], v[140:141], 1.0 op_sel_hi:[1,0]
	v_rcp_f32_e32 v140, v133
	v_mul_f32_e32 v133, 0xbfb8aa3b, v17
	v_min_f32_e32 v133, 0x42700000, v133
	v_exp_f32_e32 v133, v133
	v_pk_mul_f32 v[136:137], v[142:143], v[134:135]
	v_min_f32_e32 v138, 0x42700000, v138
	v_min_f32_e32 v139, 0x42700000, v139
	v_add_f32_e32 v133, 1.0, v133
	v_rcp_f32_e32 v141, v133
	v_mul_f32_e32 v133, 0xbfb8aa3b, v10
	v_min_f32_e32 v133, 0x42700000, v133
	v_exp_f32_e32 v133, v133
	v_exp_f32_e32 v138, v138
	v_exp_f32_e32 v139, v139
	v_rcp_f32_e32 v154, v134
	v_add_f32_e32 v133, 1.0, v133
	v_rcp_f32_e32 v142, v133
	v_mul_f32_e32 v133, 0xbfb8aa3b, v11
	v_min_f32_e32 v133, 0x42700000, v133
	v_exp_f32_e32 v133, v133
	v_rcp_f32_e32 v167, v135
	v_pk_add_f32 v[134:135], v[138:139], 1.0 op_sel_hi:[1,0]
	v_add_u32_e32 v132, 0xb0, v132
	v_add_f32_e32 v133, 1.0, v133
	v_rcp_f32_e32 v143, v133
	v_mul_f32_e32 v133, 0xbfb8aa3b, v12
	v_min_f32_e32 v133, 0x42700000, v133
	v_exp_f32_e32 v133, v133
	v_pk_mul_f32 v[138:139], v[140:141], v[134:135]
	v_mul_f32_e32 v140, 0xbfb8aa3b, v2
	v_mul_f32_e32 v141, 0xbfb8aa3b, v3
	v_min_f32_e32 v140, 0x42700000, v140
	v_min_f32_e32 v141, 0x42700000, v141
	v_exp_f32_e32 v140, v140
	v_exp_f32_e32 v141, v141
	v_add_f32_e32 v133, 1.0, v133
	v_rcp_f32_e32 v144, v133
	v_mul_f32_e32 v133, 0xbfb8aa3b, v13
	v_min_f32_e32 v133, 0x42700000, v133
	v_exp_f32_e32 v133, v133
	v_rcp_f32_e32 v168, v134
	v_rcp_f32_e32 v169, v135
	v_pk_add_f32 v[134:135], v[140:141], 1.0 op_sel_hi:[1,0]
	v_add_f32_e32 v133, 1.0, v133
	v_pk_mul_f32 v[140:141], v[142:143], v[134:135]
	v_mul_f32_e32 v142, 0xbfb8aa3b, v4
	v_mul_f32_e32 v143, 0xbfb8aa3b, v5
	v_min_f32_e32 v142, 0x42700000, v142
	v_min_f32_e32 v143, 0x42700000, v143
	v_exp_f32_e32 v142, v142
	v_exp_f32_e32 v143, v143
	v_rcp_f32_e32 v145, v133
	v_rcp_f32_e32 v170, v134
	v_rcp_f32_e32 v171, v135
	v_pk_add_f32 v[134:135], v[142:143], 1.0 op_sel_hi:[1,0]
	v_ashrrev_i32_e32 v133, 31, v132
	v_pk_mul_f32 v[142:143], v[144:145], v[134:135]
	v_rcp_f32_e32 v144, v134
	v_rcp_f32_e32 v145, v135
	v_cvt_pk_bf16_f32 v135, v138, v139
	v_lshlrev_b64 v[138:139], 11, v[132:133]
	v_lshl_add_u64 v[132:133], s[68:69], 0, v[138:139]
	v_cvt_pk_bf16_f32 v134, v136, v137
	v_cvt_pk_bf16_f32 v136, v140, v141
	v_cvt_pk_bf16_f32 v137, v142, v143
	v_lshl_add_u64 v[132:133], v[132:133], 0, v[130:131]
	global_store_dwordx4 v[132:133], v[134:137], off offset:-4096 nt
	v_cvt_pk_bf16_f32 v132, v154, v167
	v_cvt_pk_bf16_f32 v133, v168, v169
	v_lshl_add_u64 v[136:137], s[70:71], 0, v[138:139]
	v_cvt_pk_bf16_f32 v134, v170, v171
	v_cvt_pk_bf16_f32 v135, v144, v145
	v_lshl_add_u64 v[130:131], v[136:137], 0, v[130:131]
	global_store_dwordx4 v[130:131], v[132:135], off offset:-4096 nt

; __device__ __forceinline__ float fast_silu(float v) { return v * fast_sigmoid(v); }
; __device__ __forceinline__ u32x4 pack8f(const f32x4 a, const f32x4 b) { u32x4 w; w.x = cvt_pk_bf16(a[0], a[1]); w.y = cvt_pk_bf16(a[2], a[3]); w.z = cvt_pk_bf16(b[0], b[1]); w.w = cvt_pk_bf16(b[2], b[3]); return w; }
;     __device__ __forceinline__ void operator()(f32x4 (&acc)[2][2][4][2], const Unit& u, int wr, int wc, int fr, int fq) const {
;     ...
;         } else if (pn < 8) {
; #pragma unroll
;             for (int ai = 0; ai < 2; ++ai)
; #pragma unroll
;                 for (int m = 0; m < 4; ++m) { const int rl = rl0 + 128 * ai + 16 * m;
; #pragma unroll
;                     for (int bj = 0; bj < 2; ++bj) { f32x4 a = acc[ai][bj][m][0], c = acc[ai][bj][m][1];
; #pragma unroll
;                         for (int i = 0; i < 4; ++i) { a[i] = fast_silu(a[i]); c[i] = fast_silu(c[i]); }
;                         *(u32x4*)(SG + (size_t)(u.pm * 256 + rl) * AW + (pn - 6) * 256 + 128 * bj + 32 * wc + 8 * fq) = pack8f(a, c); }
;                 }
.LBB0_168:
	s_andn2_b64 vcc, exec, s[88:89]
	s_cbranch_vccnz .LBB0_170
	s_mov_b32 s100, 1
	v_mul_f32_e32 v131, 0xbfb8aa3b, v122
	v_mul_f32_e32 v134, 0xbfb8aa3b, v127
	v_exp_f32_e32 v131, v131
	v_exp_f32_e32 v135, v134
	v_mul_f32_e32 v134, 0xbfb8aa3b, v123
	v_exp_f32_e32 v136, v134
	v_mul_f32_e32 v130, 0xbfb8aa3b, v126
	v_exp_f32_e32 v130, v130
	v_add_f32_e32 v131, 1.0, v131
	v_mul_f32_e32 v137, 0xbfb8aa3b, v124
	v_mul_f32_e32 v138, 0xbfb8aa3b, v129
	v_rcp_f32_e32 v134, v131
	v_add_f32_e32 v131, 1.0, v135
	v_add_f32_e32 v135, 1.0, v136
	v_mul_f32_e32 v136, 0xbfb8aa3b, v128
	v_exp_f32_e32 v137, v137
	v_exp_f32_e32 v139, v138
	v_mul_f32_e32 v138, 0xbfb8aa3b, v125
	v_exp_f32_e32 v136, v136
	v_exp_f32_e32 v140, v138
	v_add_f32_e32 v130, 1.0, v130
	v_rcp_f32_e32 v130, v130
	v_rcp_f32_e32 v131, v131
	v_add_f32_e32 v137, 1.0, v137
	v_rcp_f32_e32 v135, v135
	v_add_f32_e32 v136, 1.0, v136
	v_rcp_f32_e32 v138, v137
	v_add_f32_e32 v137, 1.0, v139
	v_add_f32_e32 v139, 1.0, v140
	v_rcp_f32_e32 v136, v136
	v_rcp_f32_e32 v137, v137
	v_rcp_f32_e32 v139, v139
	v_pk_mul_f32 v[130:131], v[126:127], v[130:131]
	v_pk_mul_f32 v[140:141], v[122:123], v[134:135]
	v_cvt_pk_bf16_f32 v134, v130, v131
	v_add_u32_e32 v130, s1, v166
	v_pk_mul_f32 v[136:137], v[128:129], v[136:137]
	v_pk_mul_f32 v[138:139], v[124:125], v[138:139]
	v_ashrrev_i32_e32 v131, 31, v130
	v_cvt_pk_bf16_f32 v135, v136, v137
	v_cvt_pk_bf16_f32 v137, v138, v139
	v_lshlrev_b64 v[138:139], 10, v[130:131]
	v_lshlrev_b32_e32 v132, 3, v200
	v_lshl_add_u64 v[138:139], s[62:63], 0, v[138:139]
	s_lshl_b32 s22, s10, 9
	v_ashrrev_i32_e32 v133, 31, v132
	v_lshl_add_u64 v[138:139], v[138:139], 0, s[22:23]
	s_mov_b32 s79, s23
	v_lshl_add_u64 v[138:139], v[138:139], 0, s[78:79]
	v_lshlrev_b64 v[132:133], 1, v[132:133]
	v_mul_f32_e32 v131, 0xbfb8aa3b, v118
	v_cvt_pk_bf16_f32 v136, v140, v141
	v_lshl_add_u64 v[138:139], v[138:139], 0, v[132:133]
	v_exp_f32_e32 v131, v131
	v_mul_f32_e32 v140, 0xbfb8aa3b, v114
	v_exp_f32_e32 v140, v140
	global_store_dwordx4 v[138:139], v[134:137], off offset:-3072
	v_add_f32_e32 v131, 1.0, v131
	v_mul_f32_e32 v142, 0xbfb8aa3b, v117
	v_mul_f32_e32 v135, 0xbfb8aa3b, v119
	v_exp_f32_e32 v135, v135
	v_mul_f32_e32 v136, 0xbfb8aa3b, v115
	v_exp_f32_e32 v137, v136
	v_rcp_f32_e32 v134, v131
	v_add_f32_e32 v131, 1.0, v140
	v_rcp_f32_e32 v136, v131
	v_add_f32_e32 v131, 1.0, v135
	v_rcp_f32_e32 v135, v131
	v_add_f32_e32 v131, 1.0, v137
	v_mul_f32_e32 v137, 0xbfb8aa3b, v120
	v_exp_f32_e32 v140, v137
	v_mul_f32_e32 v137, 0xbfb8aa3b, v116
	v_exp_f32_e32 v141, v137
	v_rcp_f32_e32 v137, v131
	v_add_f32_e32 v131, 1.0, v140
	v_rcp_f32_e32 v140, v131
	v_add_f32_e32 v131, 1.0, v141
	v_mul_f32_e32 v141, 0xbfb8aa3b, v121
	v_exp_f32_e32 v141, v141
	v_exp_f32_e32 v143, v142
	v_rcp_f32_e32 v142, v131
	v_pk_mul_f32 v[134:135], v[118:119], v[134:135]
	v_add_f32_e32 v131, 1.0, v141
	v_rcp_f32_e32 v141, v131
	v_add_f32_e32 v131, 1.0, v143
	v_rcp_f32_e32 v143, v131
	v_pk_mul_f32 v[136:137], v[114:115], v[136:137]
	v_pk_mul_f32 v[140:141], v[120:121], v[140:141]
	v_mul_f32_e32 v131, 0xbfb8aa3b, v110
	v_pk_mul_f32 v[142:143], v[116:117], v[142:143]
	v_cvt_pk_bf16_f32 v134, v134, v135
	v_cvt_pk_bf16_f32 v135, v140, v141
	v_cvt_pk_bf16_f32 v136, v136, v137
	v_cvt_pk_bf16_f32 v137, v142, v143
	v_exp_f32_e32 v131, v131
	v_mul_f32_e32 v140, 0xbfb8aa3b, v106
	v_exp_f32_e32 v140, v140
	global_store_dwordx4 v[138:139], v[134:137], off offset:-2816
	v_add_f32_e32 v131, 1.0, v131
	v_mul_f32_e32 v142, 0xbfb8aa3b, v101
	v_mul_f32_e32 v135, 0xbfb8aa3b, v111
	v_exp_f32_e32 v135, v135
	v_mul_f32_e32 v136, 0xbfb8aa3b, v107
	v_exp_f32_e32 v137, v136
	v_rcp_f32_e32 v134, v131
	v_add_f32_e32 v131, 1.0, v140
	v_rcp_f32_e32 v136, v131
	v_add_f32_e32 v131, 1.0, v135
	v_rcp_f32_e32 v135, v131
	v_add_f32_e32 v131, 1.0, v137
	v_mul_f32_e32 v137, 0xbfb8aa3b, v112
	v_exp_f32_e32 v138, v137
	v_mul_f32_e32 v137, 0xbfb8aa3b, v108
	v_exp_f32_e32 v139, v137
	v_rcp_f32_e32 v137, v131
	v_add_f32_e32 v131, 1.0, v138
	v_rcp_f32_e32 v138, v131
	v_add_f32_e32 v131, 1.0, v139
	v_mul_f32_e32 v139, 0xbfb8aa3b, v113
	v_exp_f32_e32 v139, v139
	v_mul_f32_e32 v140, 0xbfb8aa3b, v109
	v_exp_f32_e32 v141, v140
	v_rcp_f32_e32 v140, v131
	v_add_f32_e32 v131, 1.0, v139
	v_rcp_f32_e32 v139, v131
	v_pk_mul_f32 v[134:135], v[110:111], v[134:135]
	v_add_f32_e32 v131, 1.0, v141
	v_cvt_pk_bf16_f32 v134, v134, v135
	v_pk_mul_f32 v[138:139], v[112:113], v[138:139]
	v_rcp_f32_e32 v141, v131
	v_cvt_pk_bf16_f32 v135, v138, v139
	v_add_u32_e32 v138, 16, v130
	v_ashrrev_i32_e32 v139, 31, v138
	v_lshlrev_b64 v[138:139], 10, v[138:139]
	v_lshl_add_u64 v[138:139], s[62:63], 0, v[138:139]
	v_lshl_add_u64 v[138:139], v[138:139], 0, s[22:23]
	v_pk_mul_f32 v[136:137], v[106:107], v[136:137]
	v_pk_mul_f32 v[140:141], v[108:109], v[140:141]
	v_lshl_add_u64 v[138:139], v[138:139], 0, s[78:79]
	v_mul_f32_e32 v131, 0xbfb8aa3b, v102
	v_cvt_pk_bf16_f32 v136, v136, v137
	v_cvt_pk_bf16_f32 v137, v140, v141
	v_lshl_add_u64 v[138:139], v[138:139], 0, v[132:133]
	v_exp_f32_e32 v131, v131
	v_mul_f32_e32 v140, 0xbfb8aa3b, v98
	v_exp_f32_e32 v140, v140
	global_store_dwordx4 v[138:139], v[134:137], off offset:-3072
	v_add_f32_e32 v131, 1.0, v131
	v_exp_f32_e32 v143, v142
	v_mul_f32_e32 v135, 0xbfb8aa3b, v103
	v_exp_f32_e32 v135, v135
	v_mul_f32_e32 v136, 0xbfb8aa3b, v99
	v_exp_f32_e32 v137, v136
	v_rcp_f32_e32 v134, v131
	v_add_f32_e32 v131, 1.0, v140
	v_rcp_f32_e32 v136, v131
	v_add_f32_e32 v131, 1.0, v135
	v_rcp_f32_e32 v135, v131
	v_add_f32_e32 v131, 1.0, v137
	v_mul_f32_e32 v137, 0xbfb8aa3b, v104
	v_exp_f32_e32 v140, v137
	v_mul_f32_e32 v137, 0xbfb8aa3b, v100
	v_exp_f32_e32 v141, v137
; __device__ __forceinline__ float fast_silu(float v) { return v * fast_sigmoid(v); }
; __device__ __forceinline__ u32x4 pack8f(const f32x4 a, const f32x4 b) { u32x4 w; w.x = cvt_pk_bf16(a[0], a[1]); w.y = cvt_pk_bf16(a[2], a[3]); w.z = cvt_pk_bf16(b[0], b[1]); w.w = cvt_pk_bf16(b[2], b[3]); return w; }
;     __device__ __forceinline__ void operator()(f32x4 (&acc)[2][2][4][2], const Unit& u, int wr, int wc, int fr, int fq) const {
;     ...
;             for (int ai = 0; ai < 2; ++ai)
; #pragma unroll
;                 for (int m = 0; m < 4; ++m) { const int rl = rl0 + 128 * ai + 16 * m;
; #pragma unroll
;                     for (int bj = 0; bj < 2; ++bj) { f32x4 a = acc[ai][bj][m][0], c = acc[ai][bj][m][1];
; #pragma unroll
;                         for (int i = 0; i < 4; ++i) { a[i] = fast_silu(a[i]); c[i] = fast_silu(c[i]); }
;                         *(u32x4*)(SG + (size_t)(u.pm * 256 + rl) * AW + (pn - 6) * 256 + 128 * bj + 32 * wc + 8 * fq) = pack8f(a, c); }
;                 }
	v_rcp_f32_e32 v137, v131
	v_add_f32_e32 v131, 1.0, v140
	v_rcp_f32_e32 v140, v131
	v_add_f32_e32 v131, 1.0, v141
	v_mul_f32_e32 v141, 0xbfb8aa3b, v105
	v_exp_f32_e32 v141, v141
	v_rcp_f32_e32 v142, v131
	v_pk_mul_f32 v[134:135], v[102:103], v[134:135]
	v_pk_mul_f32 v[136:137], v[98:99], v[136:137]
	v_add_f32_e32 v131, 1.0, v141
	v_rcp_f32_e32 v141, v131
	v_add_f32_e32 v131, 1.0, v143
	v_rcp_f32_e32 v143, v131
	v_mul_f32_e32 v131, 0xbfb8aa3b, v94
	v_pk_mul_f32 v[140:141], v[104:105], v[140:141]
	v_cvt_pk_bf16_f32 v134, v134, v135
	v_pk_mul_f32 v[142:143], v[100:101], v[142:143]
	v_cvt_pk_bf16_f32 v135, v140, v141
	v_cvt_pk_bf16_f32 v136, v136, v137
	v_cvt_pk_bf16_f32 v137, v142, v143
	v_exp_f32_e32 v131, v131
	v_mul_f32_e32 v140, 0xbfb8aa3b, v90
	v_exp_f32_e32 v140, v140
	global_store_dwordx4 v[138:139], v[134:137], off offset:-2816
	v_add_f32_e32 v131, 1.0, v131
	v_mul_f32_e32 v142, 0xbfb8aa3b, v85
	v_mul_f32_e32 v135, 0xbfb8aa3b, v95
	v_exp_f32_e32 v135, v135
	v_mul_f32_e32 v136, 0xbfb8aa3b, v91
	v_exp_f32_e32 v137, v136
	v_rcp_f32_e32 v134, v131
	v_add_f32_e32 v131, 1.0, v140
	v_rcp_f32_e32 v136, v131
	v_add_f32_e32 v131, 1.0, v135
	v_rcp_f32_e32 v135, v131
	v_add_f32_e32 v131, 1.0, v137
	v_mul_f32_e32 v137, 0xbfb8aa3b, v96
	v_exp_f32_e32 v138, v137
	v_mul_f32_e32 v137, 0xbfb8aa3b, v92
	v_exp_f32_e32 v139, v137
	v_rcp_f32_e32 v137, v131
	v_add_f32_e32 v131, 1.0, v138
	v_rcp_f32_e32 v138, v131
	v_add_f32_e32 v131, 1.0, v139
	v_mul_f32_e32 v139, 0xbfb8aa3b, v97
	v_exp_f32_e32 v139, v139
	v_mul_f32_e32 v140, 0xbfb8aa3b, v93
	v_exp_f32_e32 v141, v140
	v_rcp_f32_e32 v140, v131
	v_add_f32_e32 v131, 1.0, v139
	v_rcp_f32_e32 v139, v131
	v_pk_mul_f32 v[134:135], v[94:95], v[134:135]
	v_add_f32_e32 v131, 1.0, v141
	v_cvt_pk_bf16_f32 v134, v134, v135
	v_pk_mul_f32 v[138:139], v[96:97], v[138:139]
	v_rcp_f32_e32 v141, v131
	v_cvt_pk_bf16_f32 v135, v138, v139
	v_add_u32_e32 v138, 32, v130
	v_ashrrev_i32_e32 v139, 31, v138
	v_lshlrev_b64 v[138:139], 10, v[138:139]
	v_lshl_add_u64 v[138:139], s[62:63], 0, v[138:139]
	v_lshl_add_u64 v[138:139], v[138:139], 0, s[22:23]
	v_pk_mul_f32 v[136:137], v[90:91], v[136:137]
	v_pk_mul_f32 v[140:141], v[92:93], v[140:141]
	v_lshl_add_u64 v[138:139], v[138:139], 0, s[78:79]
	v_mul_f32_e32 v131, 0xbfb8aa3b, v86
	v_cvt_pk_bf16_f32 v136, v136, v137
	v_cvt_pk_bf16_f32 v137, v140, v141
	v_lshl_add_u64 v[138:139], v[138:139], 0, v[132:133]
	v_exp_f32_e32 v131, v131
	v_mul_f32_e32 v140, 0xbfb8aa3b, v82
	v_exp_f32_e32 v140, v140
	global_store_dwordx4 v[138:139], v[134:137], off offset:-3072
	v_add_f32_e32 v131, 1.0, v131
	v_exp_f32_e32 v143, v142
	v_mul_f32_e32 v135, 0xbfb8aa3b, v87
	v_exp_f32_e32 v135, v135
	v_mul_f32_e32 v136, 0xbfb8aa3b, v83
	v_exp_f32_e32 v137, v136
	v_rcp_f32_e32 v134, v131
	v_add_f32_e32 v131, 1.0, v140
	v_rcp_f32_e32 v136, v131
	v_add_f32_e32 v131, 1.0, v135
	v_rcp_f32_e32 v135, v131
	v_add_f32_e32 v131, 1.0, v137
	v_mul_f32_e32 v137, 0xbfb8aa3b, v88
	v_exp_f32_e32 v140, v137
	v_mul_f32_e32 v137, 0xbfb8aa3b, v84
	v_exp_f32_e32 v141, v137
	v_rcp_f32_e32 v137, v131
	v_add_f32_e32 v131, 1.0, v140
	v_rcp_f32_e32 v140, v131
	v_add_f32_e32 v131, 1.0, v141
	v_mul_f32_e32 v141, 0xbfb8aa3b, v89
	v_exp_f32_e32 v141, v141
	v_rcp_f32_e32 v142, v131
	v_pk_mul_f32 v[134:135], v[86:87], v[134:135]
	v_pk_mul_f32 v[136:137], v[82:83], v[136:137]
	v_add_f32_e32 v131, 1.0, v141
	v_rcp_f32_e32 v141, v131
	v_add_f32_e32 v131, 1.0, v143
	v_rcp_f32_e32 v143, v131
	v_mul_f32_e32 v131, 0xbfb8aa3b, v78
	v_pk_mul_f32 v[140:141], v[88:89], v[140:141]
	v_cvt_pk_bf16_f32 v134, v134, v135
	v_pk_mul_f32 v[142:143], v[84:85], v[142:143]
	v_cvt_pk_bf16_f32 v135, v140, v141
	v_cvt_pk_bf16_f32 v136, v136, v137
	v_cvt_pk_bf16_f32 v137, v142, v143
	v_exp_f32_e32 v131, v131
	v_mul_f32_e32 v140, 0xbfb8aa3b, v74
	v_exp_f32_e32 v140, v140
	global_store_dwordx4 v[138:139], v[134:137], off offset:-2816
	v_add_f32_e32 v131, 1.0, v131
	v_mul_f32_e32 v142, 0xbfb8aa3b, v69
	v_mul_f32_e32 v135, 0xbfb8aa3b, v79
	v_exp_f32_e32 v135, v135
	v_mul_f32_e32 v136, 0xbfb8aa3b, v75
	v_exp_f32_e32 v137, v136
	v_rcp_f32_e32 v134, v131
	v_add_f32_e32 v131, 1.0, v140
	v_rcp_f32_e32 v136, v131
	v_add_f32_e32 v131, 1.0, v135
	v_rcp_f32_e32 v135, v131
	v_add_f32_e32 v131, 1.0, v137
	v_mul_f32_e32 v137, 0xbfb8aa3b, v80
	v_exp_f32_e32 v138, v137
	v_mul_f32_e32 v137, 0xbfb8aa3b, v76
	v_exp_f32_e32 v139, v137
	v_rcp_f32_e32 v137, v131
	v_add_f32_e32 v131, 1.0, v138
	v_rcp_f32_e32 v138, v131
	v_add_f32_e32 v131, 1.0, v139
	v_mul_f32_e32 v139, 0xbfb8aa3b, v81
	v_exp_f32_e32 v139, v139
	v_mul_f32_e32 v140, 0xbfb8aa3b, v77
	v_exp_f32_e32 v141, v140
	v_rcp_f32_e32 v140, v131
	v_add_f32_e32 v131, 1.0, v139
	v_rcp_f32_e32 v139, v131
	v_pk_mul_f32 v[134:135], v[78:79], v[134:135]
	v_add_f32_e32 v131, 1.0, v141
	v_cvt_pk_bf16_f32 v134, v134, v135
	v_pk_mul_f32 v[138:139], v[80:81], v[138:139]
	v_rcp_f32_e32 v141, v131
	v_cvt_pk_bf16_f32 v135, v138, v139
	v_add_u32_e32 v138, 48, v130
	v_ashrrev_i32_e32 v139, 31, v138
	v_lshlrev_b64 v[138:139], 10, v[138:139]
	v_lshl_add_u64 v[138:139], s[62:63], 0, v[138:139]
	v_lshl_add_u64 v[138:139], v[138:139], 0, s[22:23]
	v_pk_mul_f32 v[136:137], v[74:75], v[136:137]
	v_pk_mul_f32 v[140:141], v[76:77], v[140:141]
	v_lshl_add_u64 v[138:139], v[138:139], 0, s[78:79]
	v_mul_f32_e32 v131, 0xbfb8aa3b, v70
	v_cvt_pk_bf16_f32 v136, v136, v137
	v_cvt_pk_bf16_f32 v137, v140, v141
	v_lshl_add_u64 v[138:139], v[138:139], 0, v[132:133]
	v_exp_f32_e32 v131, v131
	v_mul_f32_e32 v140, 0xbfb8aa3b, v66
	v_exp_f32_e32 v140, v140
	global_store_dwordx4 v[138:139], v[134:137], off offset:-3072
	v_add_f32_e32 v131, 1.0, v131
	v_exp_f32_e32 v143, v142
; __device__ __forceinline__ float fast_silu(float v) { return v * fast_sigmoid(v); }
; __device__ __forceinline__ u32x4 pack8f(const f32x4 a, const f32x4 b) { u32x4 w; w.x = cvt_pk_bf16(a[0], a[1]); w.y = cvt_pk_bf16(a[2], a[3]); w.z = cvt_pk_bf16(b[0], b[1]); w.w = cvt_pk_bf16(b[2], b[3]); return w; }
;     __device__ __forceinline__ void operator()(f32x4 (&acc)[2][2][4][2], const Unit& u, int wr, int wc, int fr, int fq) const {
;     ...
;             for (int ai = 0; ai < 2; ++ai)
; #pragma unroll
;                 for (int m = 0; m < 4; ++m) { const int rl = rl0 + 128 * ai + 16 * m;
; #pragma unroll
;                     for (int bj = 0; bj < 2; ++bj) { f32x4 a = acc[ai][bj][m][0], c = acc[ai][bj][m][1];
; #pragma unroll
;                         for (int i = 0; i < 4; ++i) { a[i] = fast_silu(a[i]); c[i] = fast_silu(c[i]); }
;                         *(u32x4*)(SG + (size_t)(u.pm * 256 + rl) * AW + (pn - 6) * 256 + 128 * bj + 32 * wc + 8 * fq) = pack8f(a, c); }
;                 }
	v_mul_f32_e32 v135, 0xbfb8aa3b, v71
	v_exp_f32_e32 v135, v135
	v_mul_f32_e32 v136, 0xbfb8aa3b, v67
	v_exp_f32_e32 v137, v136
	v_rcp_f32_e32 v134, v131
	v_add_f32_e32 v131, 1.0, v140
	v_rcp_f32_e32 v136, v131
	v_add_f32_e32 v131, 1.0, v135
	v_rcp_f32_e32 v135, v131
	v_add_f32_e32 v131, 1.0, v137
	v_mul_f32_e32 v137, 0xbfb8aa3b, v72
	v_exp_f32_e32 v140, v137
	v_mul_f32_e32 v137, 0xbfb8aa3b, v68
	v_exp_f32_e32 v141, v137
	v_rcp_f32_e32 v137, v131
	v_add_f32_e32 v131, 1.0, v140
	v_rcp_f32_e32 v140, v131
	v_add_f32_e32 v131, 1.0, v141
	v_mul_f32_e32 v141, 0xbfb8aa3b, v73
	v_exp_f32_e32 v141, v141
	v_rcp_f32_e32 v142, v131
	v_pk_mul_f32 v[134:135], v[70:71], v[134:135]
	v_pk_mul_f32 v[136:137], v[66:67], v[136:137]
	v_add_f32_e32 v131, 1.0, v141
	v_rcp_f32_e32 v141, v131
	v_add_f32_e32 v131, 1.0, v143
	v_rcp_f32_e32 v143, v131
	v_mul_f32_e32 v131, 0xbfb8aa3b, v62
	v_pk_mul_f32 v[140:141], v[72:73], v[140:141]
	v_cvt_pk_bf16_f32 v134, v134, v135
	v_pk_mul_f32 v[142:143], v[68:69], v[142:143]
	v_cvt_pk_bf16_f32 v135, v140, v141
	v_cvt_pk_bf16_f32 v136, v136, v137
	v_cvt_pk_bf16_f32 v137, v142, v143
	v_exp_f32_e32 v131, v131
	v_mul_f32_e32 v140, 0xbfb8aa3b, v58
	v_exp_f32_e32 v140, v140
	global_store_dwordx4 v[138:139], v[134:137], off offset:-2816
	v_add_f32_e32 v131, 1.0, v131
	v_mul_f32_e32 v142, 0xbfb8aa3b, v53
	v_mul_f32_e32 v135, 0xbfb8aa3b, v63
	v_exp_f32_e32 v135, v135
	v_mul_f32_e32 v136, 0xbfb8aa3b, v59
	v_exp_f32_e32 v137, v136
	v_rcp_f32_e32 v134, v131
	v_add_f32_e32 v131, 1.0, v140
	v_rcp_f32_e32 v136, v131
	v_add_f32_e32 v131, 1.0, v135
	v_rcp_f32_e32 v135, v131
	v_add_f32_e32 v131, 1.0, v137
	v_mul_f32_e32 v137, 0xbfb8aa3b, v64
	v_exp_f32_e32 v138, v137
	v_mul_f32_e32 v137, 0xbfb8aa3b, v60
	v_exp_f32_e32 v139, v137
	v_rcp_f32_e32 v137, v131
	v_add_f32_e32 v131, 1.0, v138
	v_rcp_f32_e32 v138, v131
	v_add_f32_e32 v131, 1.0, v139
	v_mul_f32_e32 v139, 0xbfb8aa3b, v65
	v_exp_f32_e32 v139, v139
	v_mul_f32_e32 v140, 0xbfb8aa3b, v61
	v_exp_f32_e32 v141, v140
	v_rcp_f32_e32 v140, v131
	v_add_f32_e32 v131, 1.0, v139
	v_rcp_f32_e32 v139, v131
	v_pk_mul_f32 v[134:135], v[62:63], v[134:135]
	v_add_f32_e32 v131, 1.0, v141
	v_cvt_pk_bf16_f32 v134, v134, v135
	v_pk_mul_f32 v[138:139], v[64:65], v[138:139]
	v_rcp_f32_e32 v141, v131
	v_cvt_pk_bf16_f32 v135, v138, v139
	v_add_u32_e32 v138, 0x80, v130
	v_ashrrev_i32_e32 v139, 31, v138
	v_lshlrev_b64 v[138:139], 10, v[138:139]
	v_lshl_add_u64 v[138:139], s[62:63], 0, v[138:139]
	v_lshl_add_u64 v[138:139], v[138:139], 0, s[22:23]
	v_pk_mul_f32 v[136:137], v[58:59], v[136:137]
	v_pk_mul_f32 v[140:141], v[60:61], v[140:141]
	v_lshl_add_u64 v[138:139], v[138:139], 0, s[78:79]
	v_mul_f32_e32 v131, 0xbfb8aa3b, v54
	v_cvt_pk_bf16_f32 v136, v136, v137
	v_cvt_pk_bf16_f32 v137, v140, v141
	v_lshl_add_u64 v[138:139], v[138:139], 0, v[132:133]
	v_exp_f32_e32 v131, v131
	v_mul_f32_e32 v140, 0xbfb8aa3b, v50
	v_exp_f32_e32 v140, v140
	global_store_dwordx4 v[138:139], v[134:137], off offset:-3072
	v_add_f32_e32 v131, 1.0, v131
	v_exp_f32_e32 v143, v142
	v_mul_f32_e32 v135, 0xbfb8aa3b, v55
	v_exp_f32_e32 v135, v135
	v_mul_f32_e32 v136, 0xbfb8aa3b, v51
	v_exp_f32_e32 v137, v136
	v_rcp_f32_e32 v134, v131
	v_add_f32_e32 v131, 1.0, v140
	v_rcp_f32_e32 v136, v131
	v_add_f32_e32 v131, 1.0, v135
	v_rcp_f32_e32 v135, v131
	v_add_f32_e32 v131, 1.0, v137
	v_mul_f32_e32 v137, 0xbfb8aa3b, v56
	v_exp_f32_e32 v140, v137
	v_mul_f32_e32 v137, 0xbfb8aa3b, v52
	v_exp_f32_e32 v141, v137
	v_rcp_f32_e32 v137, v131
	v_add_f32_e32 v131, 1.0, v140
	v_rcp_f32_e32 v140, v131
	v_add_f32_e32 v131, 1.0, v141
	v_mul_f32_e32 v141, 0xbfb8aa3b, v57
	v_exp_f32_e32 v141, v141
	v_rcp_f32_e32 v142, v131
	v_pk_mul_f32 v[134:135], v[54:55], v[134:135]
	v_pk_mul_f32 v[136:137], v[50:51], v[136:137]
	v_add_f32_e32 v131, 1.0, v141
	v_rcp_f32_e32 v141, v131
	v_add_f32_e32 v131, 1.0, v143
	v_rcp_f32_e32 v143, v131
	v_mul_f32_e32 v131, 0xbfb8aa3b, v46
	v_pk_mul_f32 v[140:141], v[56:57], v[140:141]
	v_cvt_pk_bf16_f32 v134, v134, v135
	v_pk_mul_f32 v[142:143], v[52:53], v[142:143]
	v_cvt_pk_bf16_f32 v135, v140, v141
	v_cvt_pk_bf16_f32 v136, v136, v137
	v_cvt_pk_bf16_f32 v137, v142, v143
	v_exp_f32_e32 v131, v131
	v_mul_f32_e32 v140, 0xbfb8aa3b, v42
	v_exp_f32_e32 v140, v140
	global_store_dwordx4 v[138:139], v[134:137], off offset:-2816
	v_add_f32_e32 v131, 1.0, v131
	v_mul_f32_e32 v142, 0xbfb8aa3b, v37
	v_mul_f32_e32 v135, 0xbfb8aa3b, v47
	v_exp_f32_e32 v135, v135
	v_mul_f32_e32 v136, 0xbfb8aa3b, v43
	v_exp_f32_e32 v137, v136
	v_rcp_f32_e32 v134, v131
	v_add_f32_e32 v131, 1.0, v140
	v_rcp_f32_e32 v136, v131
	v_add_f32_e32 v131, 1.0, v135
	v_rcp_f32_e32 v135, v131
	v_add_f32_e32 v131, 1.0, v137
	v_mul_f32_e32 v137, 0xbfb8aa3b, v48
	v_exp_f32_e32 v138, v137
	v_mul_f32_e32 v137, 0xbfb8aa3b, v44
	v_exp_f32_e32 v139, v137
	v_rcp_f32_e32 v137, v131
	v_add_f32_e32 v131, 1.0, v138
	v_rcp_f32_e32 v138, v131
	v_add_f32_e32 v131, 1.0, v139
	v_mul_f32_e32 v139, 0xbfb8aa3b, v49
	v_exp_f32_e32 v139, v139
	v_mul_f32_e32 v140, 0xbfb8aa3b, v45
	v_exp_f32_e32 v141, v140
	v_rcp_f32_e32 v140, v131
	v_add_f32_e32 v131, 1.0, v139
	v_rcp_f32_e32 v139, v131
	v_pk_mul_f32 v[134:135], v[46:47], v[134:135]
	v_add_f32_e32 v131, 1.0, v141
	v_cvt_pk_bf16_f32 v134, v134, v135
	v_pk_mul_f32 v[138:139], v[48:49], v[138:139]
	v_rcp_f32_e32 v141, v131
	v_cvt_pk_bf16_f32 v135, v138, v139
	v_add_u32_e32 v138, 0x90, v130
	v_ashrrev_i32_e32 v139, 31, v138
	v_lshlrev_b64 v[138:139], 10, v[138:139]
	v_lshl_add_u64 v[138:139], s[62:63], 0, v[138:139]
	v_lshl_add_u64 v[138:139], v[138:139], 0, s[22:23]
	v_pk_mul_f32 v[136:137], v[42:43], v[136:137]
	v_pk_mul_f32 v[140:141], v[44:45], v[140:141]
; __device__ __forceinline__ float fast_silu(float v) { return v * fast_sigmoid(v); }
; __device__ __forceinline__ u32x4 pack8f(const f32x4 a, const f32x4 b) { u32x4 w; w.x = cvt_pk_bf16(a[0], a[1]); w.y = cvt_pk_bf16(a[2], a[3]); w.z = cvt_pk_bf16(b[0], b[1]); w.w = cvt_pk_bf16(b[2], b[3]); return w; }
;     __device__ __forceinline__ void operator()(f32x4 (&acc)[2][2][4][2], const Unit& u, int wr, int wc, int fr, int fq) const {
;     ...
;             for (int ai = 0; ai < 2; ++ai)
; #pragma unroll
;                 for (int m = 0; m < 4; ++m) { const int rl = rl0 + 128 * ai + 16 * m;
; #pragma unroll
;                     for (int bj = 0; bj < 2; ++bj) { f32x4 a = acc[ai][bj][m][0], c = acc[ai][bj][m][1];
; #pragma unroll
;                         for (int i = 0; i < 4; ++i) { a[i] = fast_silu(a[i]); c[i] = fast_silu(c[i]); }
;                         *(u32x4*)(SG + (size_t)(u.pm * 256 + rl) * AW + (pn - 6) * 256 + 128 * bj + 32 * wc + 8 * fq) = pack8f(a, c); }
;                 }
	v_lshl_add_u64 v[138:139], v[138:139], 0, s[78:79]
	v_mul_f32_e32 v131, 0xbfb8aa3b, v38
	v_cvt_pk_bf16_f32 v136, v136, v137
	v_cvt_pk_bf16_f32 v137, v140, v141
	v_lshl_add_u64 v[138:139], v[138:139], 0, v[132:133]
	v_exp_f32_e32 v131, v131
	v_mul_f32_e32 v140, 0xbfb8aa3b, v34
	v_exp_f32_e32 v140, v140
	global_store_dwordx4 v[138:139], v[134:137], off offset:-3072
	v_add_f32_e32 v131, 1.0, v131
	v_exp_f32_e32 v143, v142
	v_mul_f32_e32 v135, 0xbfb8aa3b, v39
	v_exp_f32_e32 v135, v135
	v_mul_f32_e32 v136, 0xbfb8aa3b, v35
	v_exp_f32_e32 v137, v136
	v_rcp_f32_e32 v134, v131
	v_add_f32_e32 v131, 1.0, v140
	v_rcp_f32_e32 v136, v131
	v_add_f32_e32 v131, 1.0, v135
	v_rcp_f32_e32 v135, v131
	v_add_f32_e32 v131, 1.0, v137
	v_mul_f32_e32 v137, 0xbfb8aa3b, v40
	v_exp_f32_e32 v140, v137
	v_mul_f32_e32 v137, 0xbfb8aa3b, v36
	v_exp_f32_e32 v141, v137
	v_rcp_f32_e32 v137, v131
	v_add_f32_e32 v131, 1.0, v140
	v_rcp_f32_e32 v140, v131
	v_add_f32_e32 v131, 1.0, v141
	v_mul_f32_e32 v141, 0xbfb8aa3b, v41
	v_exp_f32_e32 v141, v141
	v_rcp_f32_e32 v142, v131
	v_pk_mul_f32 v[134:135], v[38:39], v[134:135]
	v_pk_mul_f32 v[136:137], v[34:35], v[136:137]
	v_add_f32_e32 v131, 1.0, v141
	v_rcp_f32_e32 v141, v131
	v_add_f32_e32 v131, 1.0, v143
	v_rcp_f32_e32 v143, v131
	v_mul_f32_e32 v131, 0xbfb8aa3b, v30
	v_pk_mul_f32 v[140:141], v[40:41], v[140:141]
	v_cvt_pk_bf16_f32 v134, v134, v135
	v_pk_mul_f32 v[142:143], v[36:37], v[142:143]
	v_cvt_pk_bf16_f32 v135, v140, v141
	v_cvt_pk_bf16_f32 v136, v136, v137
	v_cvt_pk_bf16_f32 v137, v142, v143
	v_exp_f32_e32 v131, v131
	v_mul_f32_e32 v140, 0xbfb8aa3b, v26
	v_exp_f32_e32 v140, v140
	global_store_dwordx4 v[138:139], v[134:137], off offset:-2816
	v_add_f32_e32 v131, 1.0, v131
	v_mul_f32_e32 v142, 0xbfb8aa3b, v21
	v_mul_f32_e32 v135, 0xbfb8aa3b, v31
	v_exp_f32_e32 v135, v135
	v_mul_f32_e32 v136, 0xbfb8aa3b, v27
	v_exp_f32_e32 v137, v136
	v_rcp_f32_e32 v134, v131
	v_add_f32_e32 v131, 1.0, v140
	v_rcp_f32_e32 v136, v131
	v_add_f32_e32 v131, 1.0, v135
	v_rcp_f32_e32 v135, v131
	v_add_f32_e32 v131, 1.0, v137
	v_mul_f32_e32 v137, 0xbfb8aa3b, v32
	v_exp_f32_e32 v138, v137
	v_mul_f32_e32 v137, 0xbfb8aa3b, v28
	v_exp_f32_e32 v139, v137
	v_rcp_f32_e32 v137, v131
	v_add_f32_e32 v131, 1.0, v138
	v_rcp_f32_e32 v138, v131
	v_add_f32_e32 v131, 1.0, v139
	v_mul_f32_e32 v139, 0xbfb8aa3b, v33
	v_exp_f32_e32 v139, v139
	v_mul_f32_e32 v140, 0xbfb8aa3b, v29
	v_exp_f32_e32 v141, v140
	v_rcp_f32_e32 v140, v131
	v_add_f32_e32 v131, 1.0, v139
	v_rcp_f32_e32 v139, v131
	v_pk_mul_f32 v[134:135], v[30:31], v[134:135]
	v_add_f32_e32 v131, 1.0, v141
	v_cvt_pk_bf16_f32 v134, v134, v135
	v_pk_mul_f32 v[138:139], v[32:33], v[138:139]
	v_rcp_f32_e32 v141, v131
	v_cvt_pk_bf16_f32 v135, v138, v139
	v_add_u32_e32 v138, 0xa0, v130
	v_ashrrev_i32_e32 v139, 31, v138
	v_lshlrev_b64 v[138:139], 10, v[138:139]
	v_lshl_add_u64 v[138:139], s[62:63], 0, v[138:139]
	v_lshl_add_u64 v[138:139], v[138:139], 0, s[22:23]
	v_pk_mul_f32 v[136:137], v[26:27], v[136:137]
	v_pk_mul_f32 v[140:141], v[28:29], v[140:141]
	v_lshl_add_u64 v[138:139], v[138:139], 0, s[78:79]
	v_mul_f32_e32 v131, 0xbfb8aa3b, v22
	v_cvt_pk_bf16_f32 v136, v136, v137
	v_cvt_pk_bf16_f32 v137, v140, v141
	v_lshl_add_u64 v[138:139], v[138:139], 0, v[132:133]
	v_exp_f32_e32 v131, v131
	v_mul_f32_e32 v140, 0xbfb8aa3b, v18
	v_exp_f32_e32 v140, v140
	global_store_dwordx4 v[138:139], v[134:137], off offset:-3072
	v_add_f32_e32 v131, 1.0, v131
	v_exp_f32_e32 v143, v142
	v_mul_f32_e32 v135, 0xbfb8aa3b, v23
	v_exp_f32_e32 v135, v135
	v_mul_f32_e32 v136, 0xbfb8aa3b, v19
	v_exp_f32_e32 v137, v136
	v_rcp_f32_e32 v134, v131
	v_add_f32_e32 v131, 1.0, v140
	v_rcp_f32_e32 v136, v131
	v_add_f32_e32 v131, 1.0, v135
	v_rcp_f32_e32 v135, v131
	v_add_f32_e32 v131, 1.0, v137
	v_mul_f32_e32 v137, 0xbfb8aa3b, v24
; __device__ __forceinline__ float fast_silu(float v) { return v * fast_sigmoid(v); }
; __device__ __forceinline__ u32x4 pack8f(const f32x4 a, const f32x4 b) { u32x4 w; w.x = cvt_pk_bf16(a[0], a[1]); w.y = cvt_pk_bf16(a[2], a[3]); w.z = cvt_pk_bf16(b[0], b[1]); w.w = cvt_pk_bf16(b[2], b[3]); return w; }
;     __device__ __forceinline__ void operator()(f32x4 (&acc)[2][2][4][2], const Unit& u, int wr, int wc, int fr, int fq) const {
;     ...
;             for (int ai = 0; ai < 2; ++ai)
; #pragma unroll
;                 for (int m = 0; m < 4; ++m) { const int rl = rl0 + 128 * ai + 16 * m;
; #pragma unroll
;                     for (int bj = 0; bj < 2; ++bj) { f32x4 a = acc[ai][bj][m][0], c = acc[ai][bj][m][1];
; #pragma unroll
;                         for (int i = 0; i < 4; ++i) { a[i] = fast_silu(a[i]); c[i] = fast_silu(c[i]); }
;                         *(u32x4*)(SG + (size_t)(u.pm * 256 + rl) * AW + (pn - 6) * 256 + 128 * bj + 32 * wc + 8 * fq) = pack8f(a, c); }
;                 }
	v_exp_f32_e32 v140, v137
	v_mul_f32_e32 v137, 0xbfb8aa3b, v20
	v_exp_f32_e32 v141, v137
	v_rcp_f32_e32 v137, v131
	v_add_f32_e32 v131, 1.0, v140
	v_rcp_f32_e32 v140, v131
	v_add_f32_e32 v131, 1.0, v141
	v_mul_f32_e32 v141, 0xbfb8aa3b, v25
	v_exp_f32_e32 v141, v141
	v_rcp_f32_e32 v142, v131
	v_pk_mul_f32 v[134:135], v[22:23], v[134:135]
	v_pk_mul_f32 v[136:137], v[18:19], v[136:137]
	v_add_f32_e32 v131, 1.0, v141
	v_rcp_f32_e32 v141, v131
	v_add_f32_e32 v131, 1.0, v143
	v_rcp_f32_e32 v143, v131
	v_mul_f32_e32 v131, 0xbfb8aa3b, v14
	v_pk_mul_f32 v[140:141], v[24:25], v[140:141]
	v_cvt_pk_bf16_f32 v134, v134, v135
	v_pk_mul_f32 v[142:143], v[20:21], v[142:143]
	v_cvt_pk_bf16_f32 v135, v140, v141
	v_cvt_pk_bf16_f32 v136, v136, v137
	v_cvt_pk_bf16_f32 v137, v142, v143
	v_exp_f32_e32 v131, v131
	v_mul_f32_e32 v140, 0xbfb8aa3b, v10
	v_exp_f32_e32 v140, v140
	global_store_dwordx4 v[138:139], v[134:137], off offset:-2816
	v_add_f32_e32 v131, 1.0, v131
	v_add_u32_e32 v130, 0xb0, v130
	v_mul_f32_e32 v135, 0xbfb8aa3b, v15
	v_exp_f32_e32 v135, v135
	v_mul_f32_e32 v136, 0xbfb8aa3b, v11
	v_exp_f32_e32 v137, v136
	v_rcp_f32_e32 v134, v131
	v_add_f32_e32 v131, 1.0, v140
	v_rcp_f32_e32 v136, v131
	v_add_f32_e32 v131, 1.0, v135
	v_rcp_f32_e32 v135, v131
	v_add_f32_e32 v131, 1.0, v137
	v_mul_f32_e32 v137, 0xbfb8aa3b, v16
	v_exp_f32_e32 v138, v137
	v_mul_f32_e32 v137, 0xbfb8aa3b, v12
	v_exp_f32_e32 v139, v137
	v_rcp_f32_e32 v137, v131
	v_add_f32_e32 v131, 1.0, v138
	v_rcp_f32_e32 v138, v131
	v_add_f32_e32 v131, 1.0, v139
	v_mul_f32_e32 v139, 0xbfb8aa3b, v17
	v_exp_f32_e32 v139, v139
	v_mul_f32_e32 v140, 0xbfb8aa3b, v13
	v_exp_f32_e32 v141, v140
	v_rcp_f32_e32 v140, v131
	v_add_f32_e32 v131, 1.0, v139
	v_rcp_f32_e32 v139, v131
	v_add_f32_e32 v131, 1.0, v141
	v_rcp_f32_e32 v141, v131
	v_ashrrev_i32_e32 v131, 31, v130
	v_lshlrev_b64 v[130:131], 10, v[130:131]
	v_lshl_add_u64 v[130:131], s[62:63], 0, v[130:131]
	v_lshl_add_u64 v[130:131], v[130:131], 0, s[22:23]
	v_pk_mul_f32 v[134:135], v[14:15], v[134:135]
	v_pk_mul_f32 v[138:139], v[16:17], v[138:139]
	v_lshl_add_u64 v[130:131], v[130:131], 0, s[78:79]
	v_pk_mul_f32 v[136:137], v[10:11], v[136:137]
	v_pk_mul_f32 v[140:141], v[12:13], v[140:141]
	v_cvt_pk_bf16_f32 v134, v134, v135
	v_cvt_pk_bf16_f32 v135, v138, v139
	v_lshl_add_u64 v[138:139], v[130:131], 0, v[132:133]
	v_mul_f32_e32 v131, 0xbfb8aa3b, v2
	v_mul_f32_e32 v132, 0xbfb8aa3b, v7
	v_cvt_pk_bf16_f32 v136, v136, v137
	v_cvt_pk_bf16_f32 v137, v140, v141
	v_exp_f32_e32 v131, v131
	v_exp_f32_e32 v133, v132
	v_mul_f32_e32 v132, 0xbfb8aa3b, v3
	global_store_dwordx4 v[138:139], v[134:137], off offset:-3072
	v_add_f32_e32 v131, 1.0, v131
	v_mul_f32_e32 v130, 0xbfb8aa3b, v6
	v_exp_f32_e32 v134, v132
	v_mul_f32_e32 v135, 0xbfb8aa3b, v4
	v_mul_f32_e32 v136, 0xbfb8aa3b, v9
	v_rcp_f32_e32 v132, v131
	v_add_f32_e32 v131, 1.0, v133
	v_add_f32_e32 v133, 1.0, v134
	v_mul_f32_e32 v134, 0xbfb8aa3b, v8
	v_exp_f32_e32 v135, v135
	v_exp_f32_e32 v137, v136
	v_mul_f32_e32 v136, 0xbfb8aa3b, v5
	v_exp_f32_e32 v130, v130
	v_exp_f32_e32 v134, v134
	v_exp_f32_e32 v140, v136
	v_add_f32_e32 v135, 1.0, v135
	v_add_f32_e32 v130, 1.0, v130
	v_add_f32_e32 v134, 1.0, v134
	v_rcp_f32_e32 v136, v135
	v_add_f32_e32 v135, 1.0, v137
	v_add_f32_e32 v137, 1.0, v140
	v_rcp_f32_e32 v130, v130
	v_rcp_f32_e32 v131, v131
	v_rcp_f32_e32 v133, v133
	v_rcp_f32_e32 v134, v134
	v_rcp_f32_e32 v135, v135
	v_rcp_f32_e32 v137, v137
	v_pk_mul_f32 v[130:131], v[6:7], v[130:131]
	v_pk_mul_f32 v[132:133], v[2:3], v[132:133]
	v_pk_mul_f32 v[134:135], v[8:9], v[134:135]
	v_pk_mul_f32 v[136:137], v[4:5], v[136:137]
	v_cvt_pk_bf16_f32 v130, v130, v131
	v_cvt_pk_bf16_f32 v131, v134, v135
	v_cvt_pk_bf16_f32 v132, v132, v133
	v_cvt_pk_bf16_f32 v133, v136, v137
	global_store_dwordx4 v[138:139], v[130:133], off offset:-2816

; __device__ __forceinline__ u32x4 pack8f(const f32x4 a, const f32x4 b) { u32x4 w; w.x = cvt_pk_bf16(a[0], a[1]); w.y = cvt_pk_bf16(a[2], a[3]); w.z = cvt_pk_bf16(b[0], b[1]); w.w = cvt_pk_bf16(b[2], b[3]); return w; }
;     __device__ __forceinline__ void operator()(f32x4 (&acc)[2][2][4][2], const Unit& u, int wr, int wc, int fr, int fq) const {
;     ...
;         } else if (pn < 6) {
; #pragma unroll
;             for (int ai = 0; ai < 2; ++ai)
; #pragma unroll
;                 for (int m = 0; m < 4; ++m) { const int rl = rl0 + 128 * ai + 16 * m;
; #pragma unroll
;                     for (int bj = 0; bj < 2; ++bj)
;                         *(u32x4*)(VI + vimg_off(b, (pn - 4) * 2 + bj, s0 + rl + NMETA, 32 * wc + 8 * fq)) = pack8f(acc[ai][bj][m][0], acc[ai][bj][m][1]);
;                 }
.LBB0_171:
	s_andn2_b64 vcc, exec, s[88:89]
	s_cbranch_vccnz .LBB0_173
	s_mov_b32 s100, 1
	v_add_u32_e32 v144, s83, v166
	v_lshlrev_b32_e32 v132, 1, v166
	s_lshl_b32 s11, s10, 1
	v_add_u32_e32 v130, 16, v144
	v_readlane_b32 s18, v236, 22
	v_and_b32_e32 v145, 8, v132
	s_add_i32 s11, s11, -8
	v_lshl_add_u32 v131, v200, 3, s18
	s_lshl_b32 s18, s81, 2
	v_ashrrev_i32_e32 v136, 6, v130
	v_and_or_b32 v130, v130, 48, v145
	s_or_b32 s11, s18, s11
	v_ashrrev_i32_e32 v167, 5, v131
	v_ashrrev_i32_e32 v137, 31, v136
	v_lshrrev_b32_e32 v130, 1, v130
	v_lshrrev_b32_e32 v132, 1, v166
	v_and_b32_e32 v131, 3, v166
	v_add_lshl_u32 v130, v130, v167, 8
	v_mad_i64_i32 v[138:139], s[88:89], s11, v197, v[136:137]
	v_and_or_b32 v142, v132, 4, v131
	v_ashrrev_i32_e32 v131, 31, v130
	v_lshlrev_b64 v[138:139], 14, v[138:139]
	s_or_b32 s22, s11, 1
	v_lshl_add_u64 v[138:139], s[60:61], 0, v[138:139]
	v_lshlrev_b64 v[140:141], 1, v[130:131]
	v_mad_i64_i32 v[136:137], s[88:89], s22, v197, v[136:137]
	v_lshl_add_u64 v[130:131], v[138:139], 0, v[140:141]
	v_lshlrev_b32_e32 v154, 6, v142
	v_lshlrev_b64 v[136:137], 14, v[136:137]
	v_lshl_add_u64 v[138:139], v[130:131], 0, v[154:155]
	v_lshlrev_b32_e32 v130, 4, v200
	v_lshl_add_u64 v[136:137], s[60:61], 0, v[136:137]
	v_and_b32_e32 v130, 48, v130
	v_mov_b32_e32 v131, v155
	v_lshl_add_u64 v[136:137], v[136:137], 0, v[140:141]
	v_cvt_pk_bf16_f32 v132, v126, v127
	v_cvt_pk_bf16_f32 v133, v128, v129
	v_cvt_pk_bf16_f32 v134, v122, v123
	v_cvt_pk_bf16_f32 v135, v124, v125
	v_lshl_add_u64 v[138:139], v[138:139], 0, v[130:131]
	v_lshl_add_u64 v[136:137], v[136:137], 0, v[154:155]
	global_store_dwordx4 v[138:139], v[132:135], off
	v_lshl_add_u64 v[136:137], v[136:137], 0, v[130:131]
	s_nop 0
	v_cvt_pk_bf16_f32 v132, v118, v119
	v_cvt_pk_bf16_f32 v133, v120, v121
	v_cvt_pk_bf16_f32 v134, v114, v115
	v_cvt_pk_bf16_f32 v135, v116, v117
	global_store_dwordx4 v[136:137], v[132:135], off
	s_nop 1
	v_add_u32_e32 v132, 32, v144
	v_ashrrev_i32_e32 v136, 6, v132
	v_and_or_b32 v132, v132, 48, v145
	v_ashrrev_i32_e32 v137, 31, v136
	v_lshrrev_b32_e32 v132, 1, v132
	v_add_lshl_u32 v138, v132, v167, 8
	v_mad_i64_i32 v[142:143], s[88:89], s11, v197, v[136:137]
	v_ashrrev_i32_e32 v139, 31, v138
	v_lshlrev_b64 v[142:143], 14, v[142:143]
	v_mad_i64_i32 v[136:137], s[88:89], s22, v197, v[136:137]
	v_lshl_add_u64 v[142:143], s[60:61], 0, v[142:143]
	v_lshlrev_b64 v[138:139], 1, v[138:139]
	v_lshlrev_b64 v[136:137], 14, v[136:137]
	v_lshl_add_u64 v[142:143], v[142:143], 0, v[138:139]
	v_lshl_add_u64 v[136:137], s[60:61], 0, v[136:137]
	v_lshl_add_u64 v[142:143], v[142:143], 0, v[154:155]
	v_lshl_add_u64 v[136:137], v[136:137], 0, v[138:139]
	v_cvt_pk_bf16_f32 v132, v110, v111
	v_cvt_pk_bf16_f32 v133, v112, v113
	v_cvt_pk_bf16_f32 v134, v106, v107
	v_cvt_pk_bf16_f32 v135, v108, v109
	v_lshl_add_u64 v[142:143], v[142:143], 0, v[130:131]
	v_lshl_add_u64 v[136:137], v[136:137], 0, v[154:155]
	global_store_dwordx4 v[142:143], v[132:135], off
	v_lshl_add_u64 v[136:137], v[136:137], 0, v[130:131]
	s_nop 0
	v_cvt_pk_bf16_f32 v132, v102, v103
	v_cvt_pk_bf16_f32 v133, v104, v105
	v_cvt_pk_bf16_f32 v134, v98, v99
	v_cvt_pk_bf16_f32 v135, v100, v101
	global_store_dwordx4 v[136:137], v[132:135], off
	s_nop 1
	v_add_u32_e32 v132, 48, v144
	v_ashrrev_i32_e32 v136, 6, v132
	v_and_or_b32 v132, v132, 48, v145
	v_ashrrev_i32_e32 v137, 31, v136
	v_lshrrev_b32_e32 v132, 1, v132
	v_add_lshl_u32 v138, v132, v167, 8
	v_mad_i64_i32 v[142:143], s[88:89], s11, v197, v[136:137]
	v_ashrrev_i32_e32 v139, 31, v138
	v_lshlrev_b64 v[142:143], 14, v[142:143]
	v_mad_i64_i32 v[136:137], s[88:89], s22, v197, v[136:137]
	v_lshl_add_u64 v[142:143], s[60:61], 0, v[142:143]
	v_lshlrev_b64 v[138:139], 1, v[138:139]
	v_lshlrev_b64 v[136:137], 14, v[136:137]
	v_lshl_add_u64 v[142:143], v[142:143], 0, v[138:139]
	v_lshl_add_u64 v[136:137], s[60:61], 0, v[136:137]
	v_lshl_add_u64 v[142:143], v[142:143], 0, v[154:155]
	v_lshl_add_u64 v[136:137], v[136:137], 0, v[138:139]
	v_cvt_pk_bf16_f32 v132, v94, v95
	v_cvt_pk_bf16_f32 v133, v96, v97
	v_cvt_pk_bf16_f32 v134, v90, v91
	v_cvt_pk_bf16_f32 v135, v92, v93
	v_lshl_add_u64 v[142:143], v[142:143], 0, v[130:131]
	v_lshl_add_u64 v[136:137], v[136:137], 0, v[154:155]
	global_store_dwordx4 v[142:143], v[132:135], off
	v_lshl_add_u64 v[136:137], v[136:137], 0, v[130:131]
	s_nop 0
	v_cvt_pk_bf16_f32 v132, v86, v87
	v_cvt_pk_bf16_f32 v133, v88, v89
	v_cvt_pk_bf16_f32 v134, v82, v83
	v_cvt_pk_bf16_f32 v135, v84, v85
	global_store_dwordx4 v[136:137], v[132:135], off
	s_nop 1
	v_add_u32_e32 v132, 64, v144
	v_ashrrev_i32_e32 v136, 6, v132
	v_and_or_b32 v132, v132, 48, v145
	v_ashrrev_i32_e32 v137, 31, v136
	v_lshrrev_b32_e32 v132, 1, v132
	v_add_lshl_u32 v138, v132, v167, 8
	v_mad_i64_i32 v[142:143], s[88:89], s11, v197, v[136:137]
	v_ashrrev_i32_e32 v139, 31, v138
	v_lshlrev_b64 v[142:143], 14, v[142:143]
	v_mad_i64_i32 v[136:137], s[88:89], s22, v197, v[136:137]
	v_lshl_add_u64 v[142:143], s[60:61], 0, v[142:143]
	v_lshlrev_b64 v[138:139], 1, v[138:139]
	v_lshlrev_b64 v[136:137], 14, v[136:137]
	v_lshl_add_u64 v[142:143], v[142:143], 0, v[138:139]
	v_lshl_add_u64 v[136:137], s[60:61], 0, v[136:137]
	v_lshl_add_u64 v[142:143], v[142:143], 0, v[154:155]
	v_lshl_add_u64 v[136:137], v[136:137], 0, v[138:139]
	v_cvt_pk_bf16_f32 v132, v78, v79
	v_cvt_pk_bf16_f32 v133, v80, v81
	v_cvt_pk_bf16_f32 v134, v74, v75
	v_cvt_pk_bf16_f32 v135, v76, v77
; __device__ __forceinline__ u32x4 pack8f(const f32x4 a, const f32x4 b) { u32x4 w; w.x = cvt_pk_bf16(a[0], a[1]); w.y = cvt_pk_bf16(a[2], a[3]); w.z = cvt_pk_bf16(b[0], b[1]); w.w = cvt_pk_bf16(b[2], b[3]); return w; }
;     __device__ __forceinline__ void operator()(f32x4 (&acc)[2][2][4][2], const Unit& u, int wr, int wc, int fr, int fq) const {
;     ...
; #pragma unroll
;             for (int ai = 0; ai < 2; ++ai)
; #pragma unroll
;                 for (int m = 0; m < 4; ++m) { const int rl = rl0 + 128 * ai + 16 * m;
; #pragma unroll
;                     for (int bj = 0; bj < 2; ++bj)
;                         *(u32x4*)(VI + vimg_off(b, (pn - 4) * 2 + bj, s0 + rl + NMETA, 32 * wc + 8 * fq)) = pack8f(acc[ai][bj][m][0], acc[ai][bj][m][1]);
;                 }
	v_lshl_add_u64 v[142:143], v[142:143], 0, v[130:131]
	v_lshl_add_u64 v[136:137], v[136:137], 0, v[154:155]
	global_store_dwordx4 v[142:143], v[132:135], off
	v_lshl_add_u64 v[136:137], v[136:137], 0, v[130:131]
	s_nop 0
	v_cvt_pk_bf16_f32 v132, v70, v71
	v_cvt_pk_bf16_f32 v133, v72, v73
	v_cvt_pk_bf16_f32 v134, v66, v67
	v_cvt_pk_bf16_f32 v135, v68, v69
	global_store_dwordx4 v[136:137], v[132:135], off
	s_nop 1
	v_add_u32_e32 v132, 0x90, v144
	v_ashrrev_i32_e32 v136, 6, v132
	v_ashrrev_i32_e32 v137, 31, v136
	v_mad_i64_i32 v[138:139], s[88:89], s11, v197, v[136:137]
	v_lshlrev_b64 v[138:139], 14, v[138:139]
	v_mad_i64_i32 v[136:137], s[88:89], s22, v197, v[136:137]
	v_lshl_add_u64 v[138:139], s[60:61], 0, v[138:139]
	v_lshlrev_b64 v[136:137], 14, v[136:137]
	v_lshl_add_u64 v[138:139], v[138:139], 0, v[140:141]
	v_lshl_add_u64 v[136:137], s[60:61], 0, v[136:137]
	v_lshl_add_u64 v[138:139], v[138:139], 0, v[154:155]
	v_lshl_add_u64 v[136:137], v[136:137], 0, v[140:141]
	v_cvt_pk_bf16_f32 v132, v62, v63
	v_cvt_pk_bf16_f32 v133, v64, v65
	v_cvt_pk_bf16_f32 v134, v58, v59
	v_cvt_pk_bf16_f32 v135, v60, v61
	v_lshl_add_u64 v[138:139], v[138:139], 0, v[130:131]
	v_lshl_add_u64 v[136:137], v[136:137], 0, v[154:155]
	global_store_dwordx4 v[138:139], v[132:135], off
	v_lshl_add_u64 v[136:137], v[136:137], 0, v[130:131]
	s_nop 0
	v_cvt_pk_bf16_f32 v132, v54, v55
	v_cvt_pk_bf16_f32 v133, v56, v57
	v_cvt_pk_bf16_f32 v134, v50, v51
	v_cvt_pk_bf16_f32 v135, v52, v53
	global_store_dwordx4 v[136:137], v[132:135], off
	s_nop 1
	v_add_u32_e32 v132, 0xa0, v144
	v_ashrrev_i32_e32 v136, 6, v132
	v_and_or_b32 v132, v132, 48, v145
	v_ashrrev_i32_e32 v137, 31, v136
	v_lshrrev_b32_e32 v132, 1, v132
	v_add_lshl_u32 v138, v132, v167, 8
	v_mad_i64_i32 v[140:141], s[88:89], s11, v197, v[136:137]
	v_ashrrev_i32_e32 v139, 31, v138
	v_lshlrev_b64 v[140:141], 14, v[140:141]
	v_mad_i64_i32 v[136:137], s[88:89], s22, v197, v[136:137]
	v_lshl_add_u64 v[140:141], s[60:61], 0, v[140:141]
	v_lshlrev_b64 v[138:139], 1, v[138:139]
	v_lshlrev_b64 v[136:137], 14, v[136:137]
	v_lshl_add_u64 v[140:141], v[140:141], 0, v[138:139]
	v_lshl_add_u64 v[136:137], s[60:61], 0, v[136:137]
	v_lshl_add_u64 v[140:141], v[140:141], 0, v[154:155]
	v_lshl_add_u64 v[136:137], v[136:137], 0, v[138:139]
	v_cvt_pk_bf16_f32 v132, v46, v47
	v_cvt_pk_bf16_f32 v133, v48, v49
	v_cvt_pk_bf16_f32 v134, v42, v43
	v_cvt_pk_bf16_f32 v135, v44, v45
	v_lshl_add_u64 v[140:141], v[140:141], 0, v[130:131]
	v_lshl_add_u64 v[136:137], v[136:137], 0, v[154:155]
	global_store_dwordx4 v[140:141], v[132:135], off
	v_lshl_add_u64 v[136:137], v[136:137], 0, v[130:131]
	s_nop 0
	v_cvt_pk_bf16_f32 v132, v38, v39
	v_cvt_pk_bf16_f32 v133, v40, v41
	v_cvt_pk_bf16_f32 v134, v34, v35
	v_cvt_pk_bf16_f32 v135, v36, v37
	global_store_dwordx4 v[136:137], v[132:135], off
	s_nop 1
	v_add_u32_e32 v132, 0xb0, v144
	v_ashrrev_i32_e32 v136, 6, v132
	v_and_or_b32 v132, v132, 48, v145
	v_ashrrev_i32_e32 v137, 31, v136
	v_lshrrev_b32_e32 v132, 1, v132
	v_add_lshl_u32 v138, v132, v167, 8
	v_mad_i64_i32 v[140:141], s[88:89], s11, v197, v[136:137]
	v_ashrrev_i32_e32 v139, 31, v138
	v_lshlrev_b64 v[140:141], 14, v[140:141]
	v_mad_i64_i32 v[136:137], s[88:89], s22, v197, v[136:137]
	v_lshl_add_u64 v[140:141], s[60:61], 0, v[140:141]
	v_lshlrev_b64 v[138:139], 1, v[138:139]
	v_lshlrev_b64 v[136:137], 14, v[136:137]
	v_lshl_add_u64 v[140:141], v[140:141], 0, v[138:139]
	v_lshl_add_u64 v[136:137], s[60:61], 0, v[136:137]
	v_lshl_add_u64 v[140:141], v[140:141], 0, v[154:155]
	v_lshl_add_u64 v[136:137], v[136:137], 0, v[138:139]
	v_cvt_pk_bf16_f32 v132, v30, v31
	v_cvt_pk_bf16_f32 v133, v32, v33
	v_cvt_pk_bf16_f32 v134, v26, v27
	v_cvt_pk_bf16_f32 v135, v28, v29
	v_lshl_add_u64 v[140:141], v[140:141], 0, v[130:131]
	v_lshl_add_u64 v[136:137], v[136:137], 0, v[154:155]
	global_store_dwordx4 v[140:141], v[132:135], off
	v_lshl_add_u64 v[136:137], v[136:137], 0, v[130:131]
	s_nop 0
	v_cvt_pk_bf16_f32 v132, v22, v23
	v_cvt_pk_bf16_f32 v133, v24, v25
	v_cvt_pk_bf16_f32 v134, v18, v19
	v_cvt_pk_bf16_f32 v135, v20, v21
	global_store_dwordx4 v[136:137], v[132:135], off
	s_nop 1
	v_add_u32_e32 v132, 0xc0, v144
	v_ashrrev_i32_e32 v136, 6, v132
	v_and_or_b32 v132, v132, 48, v145
	v_ashrrev_i32_e32 v137, 31, v136
	v_lshrrev_b32_e32 v132, 1, v132
	v_add_lshl_u32 v138, v132, v167, 8
	v_mad_i64_i32 v[140:141], s[88:89], s11, v197, v[136:137]
	v_ashrrev_i32_e32 v139, 31, v138
	v_lshlrev_b64 v[140:141], 14, v[140:141]
	v_mad_i64_i32 v[136:137], s[88:89], s22, v197, v[136:137]
	v_lshl_add_u64 v[140:141], s[60:61], 0, v[140:141]
	v_lshlrev_b64 v[138:139], 1, v[138:139]
	v_lshlrev_b64 v[136:137], 14, v[136:137]
	v_lshl_add_u64 v[140:141], v[140:141], 0, v[138:139]
	v_lshl_add_u64 v[136:137], s[60:61], 0, v[136:137]
	v_lshl_add_u64 v[140:141], v[140:141], 0, v[154:155]
	v_lshl_add_u64 v[136:137], v[136:137], 0, v[138:139]
	v_cvt_pk_bf16_f32 v132, v14, v15
	v_cvt_pk_bf16_f32 v133, v16, v17
	v_cvt_pk_bf16_f32 v134, v10, v11
	v_cvt_pk_bf16_f32 v135, v12, v13
	v_lshl_add_u64 v[140:141], v[140:141], 0, v[130:131]
	v_lshl_add_u64 v[136:137], v[136:137], 0, v[154:155]
	global_store_dwordx4 v[140:141], v[132:135], off
	v_lshl_add_u64 v[130:131], v[136:137], 0, v[130:131]
	s_nop 0
	v_cvt_pk_bf16_f32 v132, v6, v7
	v_cvt_pk_bf16_f32 v133, v8, v9
	v_cvt_pk_bf16_f32 v134, v2, v3
	v_cvt_pk_bf16_f32 v135, v4, v5
	global_store_dwordx4 v[130:131], v[132:135], off

; #define PG8_MMA(ai, bj, At, Bt) do { __builtin_amdgcn_s_setprio(1); _Pragma("unroll") for (int m = 0; m < 4; ++m) _Pragma("unroll") for (int n = 0; n < 2; ++n) _Pragma("unroll") for (int k = 0; k < 2; ++k) \
;         acc[ai][bj][m][n] = __builtin_amdgcn_mfma_f32_16x16x32_bf16(Bt[n][k], At[m][k], acc[ai][bj][m][n], 0, 0, 0); __builtin_amdgcn_s_setprio(0); } while (0)
; #define PG8_WAIT_V(n) asm volatile("s_waitcnt vmcnt(" #n ")" ::: "memory")
; #define PG8_WAIT_L(n) asm volatile("s_waitcnt lgkmcnt(" #n ")" ::: "memory")
; #define PG8_BAR __builtin_amdgcn_s_barrier()
; #define PG8_SCHED __builtin_amdgcn_sched_barrier(0)
; template <class Epi, class Sched, bool ALIGN_EPI = false, bool SP2 = false>
; __device__ __forceinline__ void gemm_phase(PG8_LAS unsigned char* lds, const Gemm g, const Sched& S, const Epi& E) {
;     ...
;             PG8_WAIT_V(8); PG8_WAIT_L(0); PG8_BAR; PG8_MMA(0, 0, At, B0); PG8_MMA(0, 1, At, B1); PG8_BAR; PG8_SCHED;
.Lp1dr_a:
	s_waitcnt vmcnt(24)
	s_branch .Lp1dr_a_back
